# v61 plus P0 transpose early-wait removal and P3b short-conv loops unrolled with all 16 row loads issued before the first wait
# baseline (speedup 1.0000x reference)
.LBB0_422:
	s_add_i32 s4, s1, 0
	s_ashr_i32 s5, s4, 31
	s_lshl_b64 s[14:15], s[4:5], 12
	v_or_b32_e32 v90, s14, v72
	v_mov_b32_e32 v91, s15
	v_lshl_add_u64 v[92:93], s[44:45], 0, v[90:91]
	v_lshl_add_u64 v[94:95], s[18:19], 0, v[90:91]
	global_load_dwordx4 v[116:119], v[92:93], off
	s_nop 0
	global_load_dwordx4 v[120:123], v[94:95], off
	s_add_i32 s4, s1, 1
	s_ashr_i32 s5, s4, 31
	s_lshl_b64 s[14:15], s[4:5], 12
	v_or_b32_e32 v90, s14, v72
	v_mov_b32_e32 v91, s15
	v_lshl_add_u64 v[92:93], s[44:45], 0, v[90:91]
	v_lshl_add_u64 v[94:95], s[18:19], 0, v[90:91]
	global_load_dwordx4 v[124:127], v[92:93], off
	s_nop 0
	global_load_dwordx4 v[128:131], v[94:95], off
	s_add_i32 s4, s1, 2
	s_ashr_i32 s5, s4, 31
	s_lshl_b64 s[14:15], s[4:5], 12
	v_or_b32_e32 v90, s14, v72
	v_mov_b32_e32 v91, s15
	v_lshl_add_u64 v[92:93], s[44:45], 0, v[90:91]
	v_lshl_add_u64 v[94:95], s[18:19], 0, v[90:91]
	global_load_dwordx4 v[132:135], v[92:93], off
	s_nop 0
	global_load_dwordx4 v[136:139], v[94:95], off
	s_add_i32 s4, s1, 3
	s_ashr_i32 s5, s4, 31
	s_lshl_b64 s[14:15], s[4:5], 12
	v_or_b32_e32 v90, s14, v72
	v_mov_b32_e32 v91, s15
	v_lshl_add_u64 v[92:93], s[44:45], 0, v[90:91]
	v_lshl_add_u64 v[94:95], s[18:19], 0, v[90:91]
	global_load_dwordx4 v[140:143], v[92:93], off
	s_nop 0
	global_load_dwordx4 v[144:147], v[94:95], off
	s_add_i32 s4, s1, 4
	s_ashr_i32 s5, s4, 31
	s_lshl_b64 s[14:15], s[4:5], 12
	v_or_b32_e32 v90, s14, v72
	v_mov_b32_e32 v91, s15
	v_lshl_add_u64 v[92:93], s[44:45], 0, v[90:91]
	v_lshl_add_u64 v[94:95], s[18:19], 0, v[90:91]
	global_load_dwordx4 v[148:151], v[92:93], off
	s_nop 0
	global_load_dwordx4 v[152:155], v[94:95], off
	s_add_i32 s4, s1, 5
	s_ashr_i32 s5, s4, 31
	s_lshl_b64 s[14:15], s[4:5], 12
	v_or_b32_e32 v90, s14, v72
	v_mov_b32_e32 v91, s15
	v_lshl_add_u64 v[92:93], s[44:45], 0, v[90:91]
	v_lshl_add_u64 v[94:95], s[18:19], 0, v[90:91]
	global_load_dwordx4 v[156:159], v[92:93], off
	s_nop 0
	global_load_dwordx4 v[160:163], v[94:95], off
	s_add_i32 s4, s1, 6
	s_ashr_i32 s5, s4, 31
	s_lshl_b64 s[14:15], s[4:5], 12
	v_or_b32_e32 v90, s14, v72
	v_mov_b32_e32 v91, s15
	v_lshl_add_u64 v[92:93], s[44:45], 0, v[90:91]
	v_lshl_add_u64 v[94:95], s[18:19], 0, v[90:91]
	global_load_dwordx4 v[164:167], v[92:93], off
	s_nop 0
	global_load_dwordx4 v[168:171], v[94:95], off
	s_add_i32 s4, s1, 7
	s_ashr_i32 s5, s4, 31
	s_lshl_b64 s[14:15], s[4:5], 12
	v_or_b32_e32 v90, s14, v72
	v_mov_b32_e32 v91, s15
	v_lshl_add_u64 v[92:93], s[44:45], 0, v[90:91]
	v_lshl_add_u64 v[94:95], s[18:19], 0, v[90:91]
	global_load_dwordx4 v[172:175], v[92:93], off
	s_nop 0
	global_load_dwordx4 v[176:179], v[94:95], off
	s_add_i32 s4, s1, 0
	s_ashr_i32 s5, s4, 31
	s_lshl_b64 s[4:5], s[4:5], 13
	s_add_u32 s4, s42, s4
	v_mov_b32_e32 v73, v39
	s_waitcnt vmcnt(18)
	v_pk_mul_f32 v[98:99], v[82:83], v[22:23]
	s_addc_u32 s5, s43, s5
	v_pk_fma_f32 v[98:99], v[74:75], v[14:15], v[98:99]
	v_mov_b32_e32 v74, v82
	v_mov_b32_e32 v75, v83
	v_lshl_add_u64 v[82:83], s[4:5], 0, v[72:73]
	v_pk_mul_f32 v[100:101], v[84:85], v[24:25]
	v_pk_mul_f32 v[102:103], v[86:87], v[18:19]
	v_pk_mul_f32 v[104:105], v[88:89], v[20:21]
	v_add_co_u32_e32 v106, vcc, 0x1000, v82
	v_pk_fma_f32 v[100:101], v[76:77], v[16:17], v[100:101]
	v_pk_fma_f32 v[102:103], v[78:79], v[10:11], v[102:103]
	v_pk_fma_f32 v[104:105], v[80:81], v[12:13], v[104:105]
	v_mov_b32_e32 v76, v84
	v_mov_b32_e32 v77, v85
	v_mov_b32_e32 v78, v86
	v_mov_b32_e32 v79, v87
	v_mov_b32_e32 v80, v88
	v_mov_b32_e32 v81, v89
	v_addc_co_u32_e32 v107, vcc, 0, v83, vcc
	s_waitcnt vmcnt(15)
	v_lshlrev_b32_e32 v82, 16, v116
	v_and_b32_e32 v83, 0xffff0000, v116
	v_lshlrev_b32_e32 v84, 16, v117
	v_and_b32_e32 v85, 0xffff0000, v117
	v_lshlrev_b32_e32 v86, 16, v118
	v_and_b32_e32 v87, 0xffff0000, v118
	v_lshlrev_b32_e32 v88, 16, v119
	v_and_b32_e32 v89, 0xffff0000, v119
	s_waitcnt vmcnt(14)
	v_lshlrev_b32_e32 v108, 16, v120
	v_and_b32_e32 v109, 0xffff0000, v120
	v_lshlrev_b32_e32 v90, 16, v121
	v_and_b32_e32 v91, 0xffff0000, v121
	v_lshlrev_b32_e32 v94, 16, v122
	v_and_b32_e32 v95, 0xffff0000, v122
	v_lshlrev_b32_e32 v92, 16, v123
	v_and_b32_e32 v93, 0xffff0000, v123
	v_pk_fma_f32 v[96:97], v[30:31], v[82:83], v[98:99]
	v_pk_fma_f32 v[98:99], v[32:33], v[84:85], v[100:101]
	v_pk_fma_f32 v[100:101], v[26:27], v[86:87], v[102:103]
	v_pk_fma_f32 v[102:103], v[28:29], v[88:89], v[104:105]
	v_pk_mul_f32 v[96:97], v[96:97], v[108:109]
	v_pk_mul_f32 v[98:99], v[98:99], v[90:91]
	v_pk_mul_f32 v[94:95], v[100:101], v[94:95]
	v_pk_mul_f32 v[100:101], v[102:103], v[92:93]
	v_cvt_pk_bf16_f32 v90, v96, v97
	v_cvt_pk_bf16_f32 v91, v98, v99
	v_cvt_pk_bf16_f32 v92, v94, v95
	v_cvt_pk_bf16_f32 v93, v100, v101
	global_store_dwordx4 v[106:107], v[90:93], off
	s_add_i32 s4, s1, 1
	s_ashr_i32 s5, s4, 31
	s_lshl_b64 s[4:5], s[4:5], 13
	s_add_u32 s4, s42, s4
	v_mov_b32_e32 v73, v39
	v_pk_mul_f32 v[98:99], v[82:83], v[22:23]
	s_addc_u32 s5, s43, s5
	v_pk_fma_f32 v[98:99], v[74:75], v[14:15], v[98:99]
	v_mov_b32_e32 v74, v82
	v_mov_b32_e32 v75, v83
	v_lshl_add_u64 v[82:83], s[4:5], 0, v[72:73]
	v_pk_mul_f32 v[100:101], v[84:85], v[24:25]
	v_pk_mul_f32 v[102:103], v[86:87], v[18:19]
	v_pk_mul_f32 v[104:105], v[88:89], v[20:21]
	v_add_co_u32_e32 v106, vcc, 0x1000, v82
	v_pk_fma_f32 v[100:101], v[76:77], v[16:17], v[100:101]
	v_pk_fma_f32 v[102:103], v[78:79], v[10:11], v[102:103]
	v_pk_fma_f32 v[104:105], v[80:81], v[12:13], v[104:105]
	v_mov_b32_e32 v76, v84
	v_mov_b32_e32 v77, v85
	v_mov_b32_e32 v78, v86
	v_mov_b32_e32 v79, v87
	v_mov_b32_e32 v80, v88
	v_mov_b32_e32 v81, v89
	v_addc_co_u32_e32 v107, vcc, 0, v83, vcc
	s_waitcnt vmcnt(13)
	v_lshlrev_b32_e32 v82, 16, v124
	v_and_b32_e32 v83, 0xffff0000, v124
	v_lshlrev_b32_e32 v84, 16, v125
	v_and_b32_e32 v85, 0xffff0000, v125
	v_lshlrev_b32_e32 v86, 16, v126
	v_and_b32_e32 v87, 0xffff0000, v126
	v_lshlrev_b32_e32 v88, 16, v127
	v_and_b32_e32 v89, 0xffff0000, v127
	s_waitcnt vmcnt(12)
	v_lshlrev_b32_e32 v108, 16, v128
	v_and_b32_e32 v109, 0xffff0000, v128
	v_lshlrev_b32_e32 v90, 16, v129
	v_and_b32_e32 v91, 0xffff0000, v129
	v_lshlrev_b32_e32 v94, 16, v130
	v_and_b32_e32 v95, 0xffff0000, v130
	v_lshlrev_b32_e32 v92, 16, v131
	v_and_b32_e32 v93, 0xffff0000, v131
	v_pk_fma_f32 v[96:97], v[30:31], v[82:83], v[98:99]
	v_pk_fma_f32 v[98:99], v[32:33], v[84:85], v[100:101]
	v_pk_fma_f32 v[100:101], v[26:27], v[86:87], v[102:103]
	v_pk_fma_f32 v[102:103], v[28:29], v[88:89], v[104:105]
	v_pk_mul_f32 v[96:97], v[96:97], v[108:109]
	v_pk_mul_f32 v[98:99], v[98:99], v[90:91]
	v_pk_mul_f32 v[94:95], v[100:101], v[94:95]
	v_pk_mul_f32 v[100:101], v[102:103], v[92:93]
	v_cvt_pk_bf16_f32 v90, v96, v97
	v_cvt_pk_bf16_f32 v91, v98, v99
	v_cvt_pk_bf16_f32 v92, v94, v95
	v_cvt_pk_bf16_f32 v93, v100, v101
	global_store_dwordx4 v[106:107], v[90:93], off
	s_add_i32 s4, s1, 2
	s_ashr_i32 s5, s4, 31
	s_lshl_b64 s[4:5], s[4:5], 13
	s_add_u32 s4, s42, s4
	v_mov_b32_e32 v73, v39
	v_pk_mul_f32 v[98:99], v[82:83], v[22:23]
	s_addc_u32 s5, s43, s5
	v_pk_fma_f32 v[98:99], v[74:75], v[14:15], v[98:99]
	v_mov_b32_e32 v74, v82
	v_mov_b32_e32 v75, v83
	v_lshl_add_u64 v[82:83], s[4:5], 0, v[72:73]
	v_pk_mul_f32 v[100:101], v[84:85], v[24:25]
	v_pk_mul_f32 v[102:103], v[86:87], v[18:19]
	v_pk_mul_f32 v[104:105], v[88:89], v[20:21]
	v_add_co_u32_e32 v106, vcc, 0x1000, v82
	v_pk_fma_f32 v[100:101], v[76:77], v[16:17], v[100:101]
	v_pk_fma_f32 v[102:103], v[78:79], v[10:11], v[102:103]
	v_pk_fma_f32 v[104:105], v[80:81], v[12:13], v[104:105]
	v_mov_b32_e32 v76, v84
	v_mov_b32_e32 v77, v85
	v_mov_b32_e32 v78, v86
	v_mov_b32_e32 v79, v87
	v_mov_b32_e32 v80, v88
	v_mov_b32_e32 v81, v89
	v_addc_co_u32_e32 v107, vcc, 0, v83, vcc
	s_waitcnt vmcnt(11)
	v_lshlrev_b32_e32 v82, 16, v132
	v_and_b32_e32 v83, 0xffff0000, v132
	v_lshlrev_b32_e32 v84, 16, v133
	v_and_b32_e32 v85, 0xffff0000, v133
	v_lshlrev_b32_e32 v86, 16, v134
	v_and_b32_e32 v87, 0xffff0000, v134
	v_lshlrev_b32_e32 v88, 16, v135
	v_and_b32_e32 v89, 0xffff0000, v135
	s_waitcnt vmcnt(10)
	v_lshlrev_b32_e32 v108, 16, v136
	v_and_b32_e32 v109, 0xffff0000, v136
	v_lshlrev_b32_e32 v90, 16, v137
	v_and_b32_e32 v91, 0xffff0000, v137
	v_lshlrev_b32_e32 v94, 16, v138
	v_and_b32_e32 v95, 0xffff0000, v138
	v_lshlrev_b32_e32 v92, 16, v139
	v_and_b32_e32 v93, 0xffff0000, v139
	v_pk_fma_f32 v[96:97], v[30:31], v[82:83], v[98:99]
	v_pk_fma_f32 v[98:99], v[32:33], v[84:85], v[100:101]
	v_pk_fma_f32 v[100:101], v[26:27], v[86:87], v[102:103]
	v_pk_fma_f32 v[102:103], v[28:29], v[88:89], v[104:105]
	v_pk_mul_f32 v[96:97], v[96:97], v[108:109]
	v_pk_mul_f32 v[98:99], v[98:99], v[90:91]
	v_pk_mul_f32 v[94:95], v[100:101], v[94:95]
	v_pk_mul_f32 v[100:101], v[102:103], v[92:93]
	v_cvt_pk_bf16_f32 v90, v96, v97
	v_cvt_pk_bf16_f32 v91, v98, v99
	v_cvt_pk_bf16_f32 v92, v94, v95
	v_cvt_pk_bf16_f32 v93, v100, v101
	global_store_dwordx4 v[106:107], v[90:93], off
	s_add_i32 s4, s1, 3
	s_ashr_i32 s5, s4, 31
	s_lshl_b64 s[4:5], s[4:5], 13
	s_add_u32 s4, s42, s4
	v_mov_b32_e32 v73, v39
	v_pk_mul_f32 v[98:99], v[82:83], v[22:23]
	s_addc_u32 s5, s43, s5
	v_pk_fma_f32 v[98:99], v[74:75], v[14:15], v[98:99]
	v_mov_b32_e32 v74, v82
	v_mov_b32_e32 v75, v83
	v_lshl_add_u64 v[82:83], s[4:5], 0, v[72:73]
	v_pk_mul_f32 v[100:101], v[84:85], v[24:25]
	v_pk_mul_f32 v[102:103], v[86:87], v[18:19]
	v_pk_mul_f32 v[104:105], v[88:89], v[20:21]
	v_add_co_u32_e32 v106, vcc, 0x1000, v82
	v_pk_fma_f32 v[100:101], v[76:77], v[16:17], v[100:101]
	v_pk_fma_f32 v[102:103], v[78:79], v[10:11], v[102:103]
	v_pk_fma_f32 v[104:105], v[80:81], v[12:13], v[104:105]
	v_mov_b32_e32 v76, v84
	v_mov_b32_e32 v77, v85
	v_mov_b32_e32 v78, v86
	v_mov_b32_e32 v79, v87
	v_mov_b32_e32 v80, v88
	v_mov_b32_e32 v81, v89
	v_addc_co_u32_e32 v107, vcc, 0, v83, vcc
	s_waitcnt vmcnt(9)
	v_lshlrev_b32_e32 v82, 16, v140
	v_and_b32_e32 v83, 0xffff0000, v140
	v_lshlrev_b32_e32 v84, 16, v141
	v_and_b32_e32 v85, 0xffff0000, v141
	v_lshlrev_b32_e32 v86, 16, v142
	v_and_b32_e32 v87, 0xffff0000, v142
	v_lshlrev_b32_e32 v88, 16, v143
	v_and_b32_e32 v89, 0xffff0000, v143
	s_waitcnt vmcnt(8)
	v_lshlrev_b32_e32 v108, 16, v144
	v_and_b32_e32 v109, 0xffff0000, v144
	v_lshlrev_b32_e32 v90, 16, v145
	v_and_b32_e32 v91, 0xffff0000, v145
	v_lshlrev_b32_e32 v94, 16, v146
	v_and_b32_e32 v95, 0xffff0000, v146
	v_lshlrev_b32_e32 v92, 16, v147
	v_and_b32_e32 v93, 0xffff0000, v147
	v_pk_fma_f32 v[96:97], v[30:31], v[82:83], v[98:99]
	v_pk_fma_f32 v[98:99], v[32:33], v[84:85], v[100:101]
	v_pk_fma_f32 v[100:101], v[26:27], v[86:87], v[102:103]
	v_pk_fma_f32 v[102:103], v[28:29], v[88:89], v[104:105]
	v_pk_mul_f32 v[96:97], v[96:97], v[108:109]
	v_pk_mul_f32 v[98:99], v[98:99], v[90:91]
	v_pk_mul_f32 v[94:95], v[100:101], v[94:95]
	v_pk_mul_f32 v[100:101], v[102:103], v[92:93]
	v_cvt_pk_bf16_f32 v90, v96, v97
	v_cvt_pk_bf16_f32 v91, v98, v99
	v_cvt_pk_bf16_f32 v92, v94, v95
	v_cvt_pk_bf16_f32 v93, v100, v101
	global_store_dwordx4 v[106:107], v[90:93], off
	s_add_i32 s4, s1, 4
	s_ashr_i32 s5, s4, 31
	s_lshl_b64 s[4:5], s[4:5], 13
	s_add_u32 s4, s42, s4
	v_mov_b32_e32 v73, v39
	v_pk_mul_f32 v[98:99], v[82:83], v[22:23]
	s_addc_u32 s5, s43, s5
	v_pk_fma_f32 v[98:99], v[74:75], v[14:15], v[98:99]
	v_mov_b32_e32 v74, v82
	v_mov_b32_e32 v75, v83
	v_lshl_add_u64 v[82:83], s[4:5], 0, v[72:73]
	v_pk_mul_f32 v[100:101], v[84:85], v[24:25]
	v_pk_mul_f32 v[102:103], v[86:87], v[18:19]
	v_pk_mul_f32 v[104:105], v[88:89], v[20:21]
	v_add_co_u32_e32 v106, vcc, 0x1000, v82
	v_pk_fma_f32 v[100:101], v[76:77], v[16:17], v[100:101]
	v_pk_fma_f32 v[102:103], v[78:79], v[10:11], v[102:103]
	v_pk_fma_f32 v[104:105], v[80:81], v[12:13], v[104:105]
	v_mov_b32_e32 v76, v84
	v_mov_b32_e32 v77, v85
	v_mov_b32_e32 v78, v86
	v_mov_b32_e32 v79, v87
	v_mov_b32_e32 v80, v88
	v_mov_b32_e32 v81, v89
	v_addc_co_u32_e32 v107, vcc, 0, v83, vcc
	s_waitcnt vmcnt(7)
	v_lshlrev_b32_e32 v82, 16, v148
	v_and_b32_e32 v83, 0xffff0000, v148
	v_lshlrev_b32_e32 v84, 16, v149
	v_and_b32_e32 v85, 0xffff0000, v149
	v_lshlrev_b32_e32 v86, 16, v150
	v_and_b32_e32 v87, 0xffff0000, v150
	v_lshlrev_b32_e32 v88, 16, v151
	v_and_b32_e32 v89, 0xffff0000, v151
	s_waitcnt vmcnt(6)
	v_lshlrev_b32_e32 v108, 16, v152
	v_and_b32_e32 v109, 0xffff0000, v152
	v_lshlrev_b32_e32 v90, 16, v153
	v_and_b32_e32 v91, 0xffff0000, v153
	v_lshlrev_b32_e32 v94, 16, v154
	v_and_b32_e32 v95, 0xffff0000, v154
	v_lshlrev_b32_e32 v92, 16, v155
	v_and_b32_e32 v93, 0xffff0000, v155
	v_pk_fma_f32 v[96:97], v[30:31], v[82:83], v[98:99]
	v_pk_fma_f32 v[98:99], v[32:33], v[84:85], v[100:101]
	v_pk_fma_f32 v[100:101], v[26:27], v[86:87], v[102:103]
	v_pk_fma_f32 v[102:103], v[28:29], v[88:89], v[104:105]
	v_pk_mul_f32 v[96:97], v[96:97], v[108:109]
	v_pk_mul_f32 v[98:99], v[98:99], v[90:91]
	v_pk_mul_f32 v[94:95], v[100:101], v[94:95]
	v_pk_mul_f32 v[100:101], v[102:103], v[92:93]
	v_cvt_pk_bf16_f32 v90, v96, v97
	v_cvt_pk_bf16_f32 v91, v98, v99
	v_cvt_pk_bf16_f32 v92, v94, v95
	v_cvt_pk_bf16_f32 v93, v100, v101
	global_store_dwordx4 v[106:107], v[90:93], off
	s_add_i32 s4, s1, 5
	s_ashr_i32 s5, s4, 31
	s_lshl_b64 s[4:5], s[4:5], 13
	s_add_u32 s4, s42, s4
	v_mov_b32_e32 v73, v39
	v_pk_mul_f32 v[98:99], v[82:83], v[22:23]
	s_addc_u32 s5, s43, s5
	v_pk_fma_f32 v[98:99], v[74:75], v[14:15], v[98:99]
	v_mov_b32_e32 v74, v82
	v_mov_b32_e32 v75, v83
	v_lshl_add_u64 v[82:83], s[4:5], 0, v[72:73]
	v_pk_mul_f32 v[100:101], v[84:85], v[24:25]
	v_pk_mul_f32 v[102:103], v[86:87], v[18:19]
	v_pk_mul_f32 v[104:105], v[88:89], v[20:21]
	v_add_co_u32_e32 v106, vcc, 0x1000, v82
	v_pk_fma_f32 v[100:101], v[76:77], v[16:17], v[100:101]
	v_pk_fma_f32 v[102:103], v[78:79], v[10:11], v[102:103]
	v_pk_fma_f32 v[104:105], v[80:81], v[12:13], v[104:105]
	v_mov_b32_e32 v76, v84
	v_mov_b32_e32 v77, v85
	v_mov_b32_e32 v78, v86
	v_mov_b32_e32 v79, v87
	v_mov_b32_e32 v80, v88
	v_mov_b32_e32 v81, v89
	v_addc_co_u32_e32 v107, vcc, 0, v83, vcc
	s_waitcnt vmcnt(5)
	v_lshlrev_b32_e32 v82, 16, v156
	v_and_b32_e32 v83, 0xffff0000, v156
	v_lshlrev_b32_e32 v84, 16, v157
	v_and_b32_e32 v85, 0xffff0000, v157
	v_lshlrev_b32_e32 v86, 16, v158
	v_and_b32_e32 v87, 0xffff0000, v158
	v_lshlrev_b32_e32 v88, 16, v159
	v_and_b32_e32 v89, 0xffff0000, v159
	s_waitcnt vmcnt(4)
	v_lshlrev_b32_e32 v108, 16, v160
	v_and_b32_e32 v109, 0xffff0000, v160
	v_lshlrev_b32_e32 v90, 16, v161
	v_and_b32_e32 v91, 0xffff0000, v161
	v_lshlrev_b32_e32 v94, 16, v162
	v_and_b32_e32 v95, 0xffff0000, v162
	v_lshlrev_b32_e32 v92, 16, v163
	v_and_b32_e32 v93, 0xffff0000, v163
	v_pk_fma_f32 v[96:97], v[30:31], v[82:83], v[98:99]
	v_pk_fma_f32 v[98:99], v[32:33], v[84:85], v[100:101]
	v_pk_fma_f32 v[100:101], v[26:27], v[86:87], v[102:103]
	v_pk_fma_f32 v[102:103], v[28:29], v[88:89], v[104:105]
	v_pk_mul_f32 v[96:97], v[96:97], v[108:109]
	v_pk_mul_f32 v[98:99], v[98:99], v[90:91]
	v_pk_mul_f32 v[94:95], v[100:101], v[94:95]
	v_pk_mul_f32 v[100:101], v[102:103], v[92:93]
	v_cvt_pk_bf16_f32 v90, v96, v97
	v_cvt_pk_bf16_f32 v91, v98, v99
	v_cvt_pk_bf16_f32 v92, v94, v95
	v_cvt_pk_bf16_f32 v93, v100, v101
	global_store_dwordx4 v[106:107], v[90:93], off
	s_add_i32 s4, s1, 6
	s_ashr_i32 s5, s4, 31
	s_lshl_b64 s[4:5], s[4:5], 13
	s_add_u32 s4, s42, s4
	v_mov_b32_e32 v73, v39
	v_pk_mul_f32 v[98:99], v[82:83], v[22:23]
	s_addc_u32 s5, s43, s5
	v_pk_fma_f32 v[98:99], v[74:75], v[14:15], v[98:99]
	v_mov_b32_e32 v74, v82
	v_mov_b32_e32 v75, v83
	v_lshl_add_u64 v[82:83], s[4:5], 0, v[72:73]
	v_pk_mul_f32 v[100:101], v[84:85], v[24:25]
	v_pk_mul_f32 v[102:103], v[86:87], v[18:19]
	v_pk_mul_f32 v[104:105], v[88:89], v[20:21]
	v_add_co_u32_e32 v106, vcc, 0x1000, v82
	v_pk_fma_f32 v[100:101], v[76:77], v[16:17], v[100:101]
	v_pk_fma_f32 v[102:103], v[78:79], v[10:11], v[102:103]
	v_pk_fma_f32 v[104:105], v[80:81], v[12:13], v[104:105]
	v_mov_b32_e32 v76, v84
	v_mov_b32_e32 v77, v85
	v_mov_b32_e32 v78, v86
	v_mov_b32_e32 v79, v87
	v_mov_b32_e32 v80, v88
	v_mov_b32_e32 v81, v89
	v_addc_co_u32_e32 v107, vcc, 0, v83, vcc
	s_waitcnt vmcnt(3)
	v_lshlrev_b32_e32 v82, 16, v164
	v_and_b32_e32 v83, 0xffff0000, v164
	v_lshlrev_b32_e32 v84, 16, v165
	v_and_b32_e32 v85, 0xffff0000, v165
	v_lshlrev_b32_e32 v86, 16, v166
	v_and_b32_e32 v87, 0xffff0000, v166
	v_lshlrev_b32_e32 v88, 16, v167
	v_and_b32_e32 v89, 0xffff0000, v167
	s_waitcnt vmcnt(2)
	v_lshlrev_b32_e32 v108, 16, v168
	v_and_b32_e32 v109, 0xffff0000, v168
	v_lshlrev_b32_e32 v90, 16, v169
	v_and_b32_e32 v91, 0xffff0000, v169
	v_lshlrev_b32_e32 v94, 16, v170
	v_and_b32_e32 v95, 0xffff0000, v170
	v_lshlrev_b32_e32 v92, 16, v171
	v_and_b32_e32 v93, 0xffff0000, v171
	v_pk_fma_f32 v[96:97], v[30:31], v[82:83], v[98:99]
	v_pk_fma_f32 v[98:99], v[32:33], v[84:85], v[100:101]
	v_pk_fma_f32 v[100:101], v[26:27], v[86:87], v[102:103]
	v_pk_fma_f32 v[102:103], v[28:29], v[88:89], v[104:105]
	v_pk_mul_f32 v[96:97], v[96:97], v[108:109]
	v_pk_mul_f32 v[98:99], v[98:99], v[90:91]
	v_pk_mul_f32 v[94:95], v[100:101], v[94:95]
	v_pk_mul_f32 v[100:101], v[102:103], v[92:93]
	v_cvt_pk_bf16_f32 v90, v96, v97
	v_cvt_pk_bf16_f32 v91, v98, v99
	v_cvt_pk_bf16_f32 v92, v94, v95
	v_cvt_pk_bf16_f32 v93, v100, v101
	global_store_dwordx4 v[106:107], v[90:93], off
	s_add_i32 s4, s1, 7
	s_ashr_i32 s5, s4, 31
	s_lshl_b64 s[4:5], s[4:5], 13
	s_add_u32 s4, s42, s4
	v_mov_b32_e32 v73, v39
	v_pk_mul_f32 v[98:99], v[82:83], v[22:23]
	s_addc_u32 s5, s43, s5
	v_pk_fma_f32 v[98:99], v[74:75], v[14:15], v[98:99]
	v_mov_b32_e32 v74, v82
	v_mov_b32_e32 v75, v83
	v_lshl_add_u64 v[82:83], s[4:5], 0, v[72:73]
	v_pk_mul_f32 v[100:101], v[84:85], v[24:25]
	v_pk_mul_f32 v[102:103], v[86:87], v[18:19]
	v_pk_mul_f32 v[104:105], v[88:89], v[20:21]
	v_add_co_u32_e32 v106, vcc, 0x1000, v82
	v_pk_fma_f32 v[100:101], v[76:77], v[16:17], v[100:101]
	v_pk_fma_f32 v[102:103], v[78:79], v[10:11], v[102:103]
	v_pk_fma_f32 v[104:105], v[80:81], v[12:13], v[104:105]
	v_mov_b32_e32 v76, v84
	v_mov_b32_e32 v77, v85
	v_mov_b32_e32 v78, v86
	v_mov_b32_e32 v79, v87
	v_mov_b32_e32 v80, v88
	v_mov_b32_e32 v81, v89
	v_addc_co_u32_e32 v107, vcc, 0, v83, vcc
	s_waitcnt vmcnt(1)
	v_lshlrev_b32_e32 v82, 16, v172
	v_and_b32_e32 v83, 0xffff0000, v172
	v_lshlrev_b32_e32 v84, 16, v173
	v_and_b32_e32 v85, 0xffff0000, v173
	v_lshlrev_b32_e32 v86, 16, v174
	v_and_b32_e32 v87, 0xffff0000, v174
	v_lshlrev_b32_e32 v88, 16, v175
	v_and_b32_e32 v89, 0xffff0000, v175
	s_waitcnt vmcnt(0)
	v_lshlrev_b32_e32 v108, 16, v176
	v_and_b32_e32 v109, 0xffff0000, v176
	v_lshlrev_b32_e32 v90, 16, v177
	v_and_b32_e32 v91, 0xffff0000, v177
	v_lshlrev_b32_e32 v94, 16, v178
	v_and_b32_e32 v95, 0xffff0000, v178
	v_lshlrev_b32_e32 v92, 16, v179
	v_and_b32_e32 v93, 0xffff0000, v179
	v_pk_fma_f32 v[96:97], v[30:31], v[82:83], v[98:99]
	v_pk_fma_f32 v[98:99], v[32:33], v[84:85], v[100:101]
	v_pk_fma_f32 v[100:101], v[26:27], v[86:87], v[102:103]
	v_pk_fma_f32 v[102:103], v[28:29], v[88:89], v[104:105]
	v_pk_mul_f32 v[96:97], v[96:97], v[108:109]
	v_pk_mul_f32 v[98:99], v[98:99], v[90:91]
	v_pk_mul_f32 v[94:95], v[100:101], v[94:95]
	v_pk_mul_f32 v[100:101], v[102:103], v[92:93]
	v_cvt_pk_bf16_f32 v90, v96, v97
	v_cvt_pk_bf16_f32 v91, v98, v99
	v_cvt_pk_bf16_f32 v92, v94, v95
	v_cvt_pk_bf16_f32 v93, v100, v101
	global_store_dwordx4 v[106:107], v[90:93], off
	s_mov_b32 s12, 8
	global_load_dwordx4 v[10:13], v[40:41], off offset:2064
	global_load_dwordx4 v[14:17], v[40:41], off offset:2048
	global_load_dwordx4 v[18:21], v[46:47], off offset:16
	global_load_dwordx4 v[22:25], v[46:47], off
	global_load_dwordx4 v[26:29], v[48:49], off offset:16
	global_load_dwordx4 v[30:33], v[48:49], off
	v_cndmask_b32_e64 v69, 0, 1, s[10:11]
	v_cmp_ne_u32_e64 s[4:5], 1, v69
	s_andn2_b64 vcc, exec, s[10:11]
	s_cbranch_vccnz .LBB0_425
	global_load_dwordx4 v[78:81], v72, s[6:7] offset:1024
	global_load_dwordx4 v[86:89], v72, s[8:9] offset:1024
	s_waitcnt vmcnt(1)
	v_lshlrev_b32_e32 v74, 16, v78
	v_and_b32_e32 v75, 0xffff0000, v78
	v_lshlrev_b32_e32 v76, 16, v79
	v_and_b32_e32 v77, 0xffff0000, v79
	v_lshlrev_b32_e32 v78, 16, v80
	v_and_b32_e32 v79, 0xffff0000, v80
	v_lshlrev_b32_e32 v80, 16, v81
	v_and_b32_e32 v81, 0xffff0000, v81
	s_waitcnt vmcnt(0)
	v_lshlrev_b32_e32 v82, 16, v86
	v_and_b32_e32 v83, 0xffff0000, v86
	v_lshlrev_b32_e32 v84, 16, v87
	v_and_b32_e32 v85, 0xffff0000, v87
	v_lshlrev_b32_e32 v86, 16, v88
	v_and_b32_e32 v87, 0xffff0000, v88
	v_lshlrev_b32_e32 v88, 16, v89
	v_and_b32_e32 v89, 0xffff0000, v89
	s_branch .LBB0_426

.LBB0_427:
	s_add_i32 s10, s1, 0
	s_ashr_i32 s11, s10, 31
	s_lshl_b64 s[14:15], s[10:11], 12
	v_or_b32_e32 v90, s14, v38
	v_mov_b32_e32 v91, s15
	v_lshl_add_u64 v[92:93], s[44:45], 0, v[90:91]
	v_lshl_add_u64 v[94:95], s[18:19], 0, v[90:91]
	global_load_dwordx4 v[116:119], v[92:93], off
	s_nop 0
	global_load_dwordx4 v[120:123], v[94:95], off
	s_add_i32 s10, s1, 1
	s_ashr_i32 s11, s10, 31
	s_lshl_b64 s[14:15], s[10:11], 12
	v_or_b32_e32 v90, s14, v38
	v_mov_b32_e32 v91, s15
	v_lshl_add_u64 v[92:93], s[44:45], 0, v[90:91]
	v_lshl_add_u64 v[94:95], s[18:19], 0, v[90:91]
	global_load_dwordx4 v[124:127], v[92:93], off
	s_nop 0
	global_load_dwordx4 v[128:131], v[94:95], off
	s_add_i32 s10, s1, 2
	s_ashr_i32 s11, s10, 31
	s_lshl_b64 s[14:15], s[10:11], 12
	v_or_b32_e32 v90, s14, v38
	v_mov_b32_e32 v91, s15
	v_lshl_add_u64 v[92:93], s[44:45], 0, v[90:91]
	v_lshl_add_u64 v[94:95], s[18:19], 0, v[90:91]
	global_load_dwordx4 v[132:135], v[92:93], off
	s_nop 0
	global_load_dwordx4 v[136:139], v[94:95], off
	s_add_i32 s10, s1, 3
	s_ashr_i32 s11, s10, 31
	s_lshl_b64 s[14:15], s[10:11], 12
	v_or_b32_e32 v90, s14, v38
	v_mov_b32_e32 v91, s15
	v_lshl_add_u64 v[92:93], s[44:45], 0, v[90:91]
	v_lshl_add_u64 v[94:95], s[18:19], 0, v[90:91]
	global_load_dwordx4 v[140:143], v[92:93], off
	s_nop 0
	global_load_dwordx4 v[144:147], v[94:95], off
	s_add_i32 s10, s1, 4
	s_ashr_i32 s11, s10, 31
	s_lshl_b64 s[14:15], s[10:11], 12
	v_or_b32_e32 v90, s14, v38
	v_mov_b32_e32 v91, s15
	v_lshl_add_u64 v[92:93], s[44:45], 0, v[90:91]
	v_lshl_add_u64 v[94:95], s[18:19], 0, v[90:91]
	global_load_dwordx4 v[148:151], v[92:93], off
	s_nop 0
	global_load_dwordx4 v[152:155], v[94:95], off
	s_add_i32 s10, s1, 5
	s_ashr_i32 s11, s10, 31
	s_lshl_b64 s[14:15], s[10:11], 12
	v_or_b32_e32 v90, s14, v38
	v_mov_b32_e32 v91, s15
	v_lshl_add_u64 v[92:93], s[44:45], 0, v[90:91]
	v_lshl_add_u64 v[94:95], s[18:19], 0, v[90:91]
	global_load_dwordx4 v[156:159], v[92:93], off
	s_nop 0
	global_load_dwordx4 v[160:163], v[94:95], off
	s_add_i32 s10, s1, 6
	s_ashr_i32 s11, s10, 31
	s_lshl_b64 s[14:15], s[10:11], 12
	v_or_b32_e32 v90, s14, v38
	v_mov_b32_e32 v91, s15
	v_lshl_add_u64 v[92:93], s[44:45], 0, v[90:91]
	v_lshl_add_u64 v[94:95], s[18:19], 0, v[90:91]
	global_load_dwordx4 v[164:167], v[92:93], off
	s_nop 0
	global_load_dwordx4 v[168:171], v[94:95], off
	s_add_i32 s10, s1, 7
	s_ashr_i32 s11, s10, 31
	s_lshl_b64 s[14:15], s[10:11], 12
	v_or_b32_e32 v90, s14, v38
	v_mov_b32_e32 v91, s15
	v_lshl_add_u64 v[92:93], s[44:45], 0, v[90:91]
	v_lshl_add_u64 v[94:95], s[18:19], 0, v[90:91]
	global_load_dwordx4 v[172:175], v[92:93], off
	s_nop 0
	global_load_dwordx4 v[176:179], v[94:95], off
	s_add_i32 s10, s1, 0
	s_ashr_i32 s11, s10, 31
	s_lshl_b64 s[10:11], s[10:11], 13
	s_add_u32 s10, s42, s10
	s_waitcnt vmcnt(18)
	v_pk_mul_f32 v[98:99], v[82:83], v[22:23]
	s_addc_u32 s11, s43, s11
	v_pk_fma_f32 v[98:99], v[74:75], v[14:15], v[98:99]
	v_mov_b32_e32 v74, v82
	v_mov_b32_e32 v75, v83
	v_lshl_add_u64 v[82:83], s[10:11], 0, v[38:39]
	v_pk_mul_f32 v[100:101], v[84:85], v[24:25]
	v_pk_mul_f32 v[102:103], v[86:87], v[18:19]
	v_pk_mul_f32 v[104:105], v[88:89], v[20:21]
	v_add_co_u32_e32 v106, vcc, 0x1000, v82
	v_pk_fma_f32 v[100:101], v[76:77], v[16:17], v[100:101]
	v_pk_fma_f32 v[102:103], v[78:79], v[10:11], v[102:103]
	v_pk_fma_f32 v[104:105], v[80:81], v[12:13], v[104:105]
	v_mov_b32_e32 v76, v84
	v_mov_b32_e32 v77, v85
	v_mov_b32_e32 v78, v86
	v_mov_b32_e32 v79, v87
	v_mov_b32_e32 v80, v88
	v_mov_b32_e32 v81, v89
	v_addc_co_u32_e32 v107, vcc, 0, v83, vcc
	s_waitcnt vmcnt(15)
	v_lshlrev_b32_e32 v82, 16, v116
	v_and_b32_e32 v83, 0xffff0000, v116
	v_lshlrev_b32_e32 v84, 16, v117
	v_and_b32_e32 v85, 0xffff0000, v117
	v_lshlrev_b32_e32 v86, 16, v118
	v_and_b32_e32 v87, 0xffff0000, v118
	v_lshlrev_b32_e32 v88, 16, v119
	v_and_b32_e32 v89, 0xffff0000, v119
	s_waitcnt vmcnt(14)
	v_lshlrev_b32_e32 v108, 16, v120
	v_and_b32_e32 v109, 0xffff0000, v120
	v_lshlrev_b32_e32 v90, 16, v121
	v_and_b32_e32 v91, 0xffff0000, v121
	v_lshlrev_b32_e32 v94, 16, v122
	v_and_b32_e32 v95, 0xffff0000, v122
	v_lshlrev_b32_e32 v92, 16, v123
	v_and_b32_e32 v93, 0xffff0000, v123
	v_pk_fma_f32 v[96:97], v[30:31], v[82:83], v[98:99]
	v_pk_fma_f32 v[98:99], v[32:33], v[84:85], v[100:101]
	v_pk_fma_f32 v[100:101], v[26:27], v[86:87], v[102:103]
	v_pk_fma_f32 v[102:103], v[28:29], v[88:89], v[104:105]
	v_pk_mul_f32 v[96:97], v[96:97], v[108:109]
	v_pk_mul_f32 v[98:99], v[98:99], v[90:91]
	v_pk_mul_f32 v[94:95], v[100:101], v[94:95]
	v_pk_mul_f32 v[100:101], v[102:103], v[92:93]
	v_cvt_pk_bf16_f32 v90, v96, v97
	v_cvt_pk_bf16_f32 v91, v98, v99
	v_cvt_pk_bf16_f32 v92, v94, v95
	v_cvt_pk_bf16_f32 v93, v100, v101
	global_store_dwordx4 v[106:107], v[90:93], off
	s_add_i32 s10, s1, 1
	s_ashr_i32 s11, s10, 31
	s_lshl_b64 s[10:11], s[10:11], 13
	s_add_u32 s10, s42, s10
	v_pk_mul_f32 v[98:99], v[82:83], v[22:23]
	s_addc_u32 s11, s43, s11
	v_pk_fma_f32 v[98:99], v[74:75], v[14:15], v[98:99]
	v_mov_b32_e32 v74, v82
	v_mov_b32_e32 v75, v83
	v_lshl_add_u64 v[82:83], s[10:11], 0, v[38:39]
	v_pk_mul_f32 v[100:101], v[84:85], v[24:25]
	v_pk_mul_f32 v[102:103], v[86:87], v[18:19]
	v_pk_mul_f32 v[104:105], v[88:89], v[20:21]
	v_add_co_u32_e32 v106, vcc, 0x1000, v82
	v_pk_fma_f32 v[100:101], v[76:77], v[16:17], v[100:101]
	v_pk_fma_f32 v[102:103], v[78:79], v[10:11], v[102:103]
	v_pk_fma_f32 v[104:105], v[80:81], v[12:13], v[104:105]
	v_mov_b32_e32 v76, v84
	v_mov_b32_e32 v77, v85
	v_mov_b32_e32 v78, v86
	v_mov_b32_e32 v79, v87
	v_mov_b32_e32 v80, v88
	v_mov_b32_e32 v81, v89
	v_addc_co_u32_e32 v107, vcc, 0, v83, vcc
	s_waitcnt vmcnt(13)
	v_lshlrev_b32_e32 v82, 16, v124
	v_and_b32_e32 v83, 0xffff0000, v124
	v_lshlrev_b32_e32 v84, 16, v125
	v_and_b32_e32 v85, 0xffff0000, v125
	v_lshlrev_b32_e32 v86, 16, v126
	v_and_b32_e32 v87, 0xffff0000, v126
	v_lshlrev_b32_e32 v88, 16, v127
	v_and_b32_e32 v89, 0xffff0000, v127
	s_waitcnt vmcnt(12)
	v_lshlrev_b32_e32 v108, 16, v128
	v_and_b32_e32 v109, 0xffff0000, v128
	v_lshlrev_b32_e32 v90, 16, v129
	v_and_b32_e32 v91, 0xffff0000, v129
	v_lshlrev_b32_e32 v94, 16, v130
	v_and_b32_e32 v95, 0xffff0000, v130
	v_lshlrev_b32_e32 v92, 16, v131
	v_and_b32_e32 v93, 0xffff0000, v131
	v_pk_fma_f32 v[96:97], v[30:31], v[82:83], v[98:99]
	v_pk_fma_f32 v[98:99], v[32:33], v[84:85], v[100:101]
	v_pk_fma_f32 v[100:101], v[26:27], v[86:87], v[102:103]
	v_pk_fma_f32 v[102:103], v[28:29], v[88:89], v[104:105]
	v_pk_mul_f32 v[96:97], v[96:97], v[108:109]
	v_pk_mul_f32 v[98:99], v[98:99], v[90:91]
	v_pk_mul_f32 v[94:95], v[100:101], v[94:95]
	v_pk_mul_f32 v[100:101], v[102:103], v[92:93]
	v_cvt_pk_bf16_f32 v90, v96, v97
	v_cvt_pk_bf16_f32 v91, v98, v99
	v_cvt_pk_bf16_f32 v92, v94, v95
	v_cvt_pk_bf16_f32 v93, v100, v101
	global_store_dwordx4 v[106:107], v[90:93], off
	s_add_i32 s10, s1, 2
	s_ashr_i32 s11, s10, 31
	s_lshl_b64 s[10:11], s[10:11], 13
	s_add_u32 s10, s42, s10
	v_pk_mul_f32 v[98:99], v[82:83], v[22:23]
	s_addc_u32 s11, s43, s11
	v_pk_fma_f32 v[98:99], v[74:75], v[14:15], v[98:99]
	v_mov_b32_e32 v74, v82
	v_mov_b32_e32 v75, v83
	v_lshl_add_u64 v[82:83], s[10:11], 0, v[38:39]
	v_pk_mul_f32 v[100:101], v[84:85], v[24:25]
	v_pk_mul_f32 v[102:103], v[86:87], v[18:19]
	v_pk_mul_f32 v[104:105], v[88:89], v[20:21]
	v_add_co_u32_e32 v106, vcc, 0x1000, v82
	v_pk_fma_f32 v[100:101], v[76:77], v[16:17], v[100:101]
	v_pk_fma_f32 v[102:103], v[78:79], v[10:11], v[102:103]
	v_pk_fma_f32 v[104:105], v[80:81], v[12:13], v[104:105]
	v_mov_b32_e32 v76, v84
	v_mov_b32_e32 v77, v85
	v_mov_b32_e32 v78, v86
	v_mov_b32_e32 v79, v87
	v_mov_b32_e32 v80, v88
	v_mov_b32_e32 v81, v89
	v_addc_co_u32_e32 v107, vcc, 0, v83, vcc
	s_waitcnt vmcnt(11)
	v_lshlrev_b32_e32 v82, 16, v132
	v_and_b32_e32 v83, 0xffff0000, v132
	v_lshlrev_b32_e32 v84, 16, v133
	v_and_b32_e32 v85, 0xffff0000, v133
	v_lshlrev_b32_e32 v86, 16, v134
	v_and_b32_e32 v87, 0xffff0000, v134
	v_lshlrev_b32_e32 v88, 16, v135
	v_and_b32_e32 v89, 0xffff0000, v135
	s_waitcnt vmcnt(10)
	v_lshlrev_b32_e32 v108, 16, v136
	v_and_b32_e32 v109, 0xffff0000, v136
	v_lshlrev_b32_e32 v90, 16, v137
	v_and_b32_e32 v91, 0xffff0000, v137
	v_lshlrev_b32_e32 v94, 16, v138
	v_and_b32_e32 v95, 0xffff0000, v138
	v_lshlrev_b32_e32 v92, 16, v139
	v_and_b32_e32 v93, 0xffff0000, v139
	v_pk_fma_f32 v[96:97], v[30:31], v[82:83], v[98:99]
	v_pk_fma_f32 v[98:99], v[32:33], v[84:85], v[100:101]
	v_pk_fma_f32 v[100:101], v[26:27], v[86:87], v[102:103]
	v_pk_fma_f32 v[102:103], v[28:29], v[88:89], v[104:105]
	v_pk_mul_f32 v[96:97], v[96:97], v[108:109]
	v_pk_mul_f32 v[98:99], v[98:99], v[90:91]
	v_pk_mul_f32 v[94:95], v[100:101], v[94:95]
	v_pk_mul_f32 v[100:101], v[102:103], v[92:93]
	v_cvt_pk_bf16_f32 v90, v96, v97
	v_cvt_pk_bf16_f32 v91, v98, v99
	v_cvt_pk_bf16_f32 v92, v94, v95
	v_cvt_pk_bf16_f32 v93, v100, v101
	global_store_dwordx4 v[106:107], v[90:93], off
	s_add_i32 s10, s1, 3
	s_ashr_i32 s11, s10, 31
	s_lshl_b64 s[10:11], s[10:11], 13
	s_add_u32 s10, s42, s10
	v_pk_mul_f32 v[98:99], v[82:83], v[22:23]
	s_addc_u32 s11, s43, s11
	v_pk_fma_f32 v[98:99], v[74:75], v[14:15], v[98:99]
	v_mov_b32_e32 v74, v82
	v_mov_b32_e32 v75, v83
	v_lshl_add_u64 v[82:83], s[10:11], 0, v[38:39]
	v_pk_mul_f32 v[100:101], v[84:85], v[24:25]
	v_pk_mul_f32 v[102:103], v[86:87], v[18:19]
	v_pk_mul_f32 v[104:105], v[88:89], v[20:21]
	v_add_co_u32_e32 v106, vcc, 0x1000, v82
	v_pk_fma_f32 v[100:101], v[76:77], v[16:17], v[100:101]
	v_pk_fma_f32 v[102:103], v[78:79], v[10:11], v[102:103]
	v_pk_fma_f32 v[104:105], v[80:81], v[12:13], v[104:105]
	v_mov_b32_e32 v76, v84
	v_mov_b32_e32 v77, v85
	v_mov_b32_e32 v78, v86
	v_mov_b32_e32 v79, v87
	v_mov_b32_e32 v80, v88
	v_mov_b32_e32 v81, v89
	v_addc_co_u32_e32 v107, vcc, 0, v83, vcc
	s_waitcnt vmcnt(9)
	v_lshlrev_b32_e32 v82, 16, v140
	v_and_b32_e32 v83, 0xffff0000, v140
	v_lshlrev_b32_e32 v84, 16, v141
	v_and_b32_e32 v85, 0xffff0000, v141
	v_lshlrev_b32_e32 v86, 16, v142
	v_and_b32_e32 v87, 0xffff0000, v142
	v_lshlrev_b32_e32 v88, 16, v143
	v_and_b32_e32 v89, 0xffff0000, v143
	s_waitcnt vmcnt(8)
	v_lshlrev_b32_e32 v108, 16, v144
	v_and_b32_e32 v109, 0xffff0000, v144
	v_lshlrev_b32_e32 v90, 16, v145
	v_and_b32_e32 v91, 0xffff0000, v145
	v_lshlrev_b32_e32 v94, 16, v146
	v_and_b32_e32 v95, 0xffff0000, v146
	v_lshlrev_b32_e32 v92, 16, v147
	v_and_b32_e32 v93, 0xffff0000, v147
	v_pk_fma_f32 v[96:97], v[30:31], v[82:83], v[98:99]
	v_pk_fma_f32 v[98:99], v[32:33], v[84:85], v[100:101]
	v_pk_fma_f32 v[100:101], v[26:27], v[86:87], v[102:103]
	v_pk_fma_f32 v[102:103], v[28:29], v[88:89], v[104:105]
	v_pk_mul_f32 v[96:97], v[96:97], v[108:109]
	v_pk_mul_f32 v[98:99], v[98:99], v[90:91]
	v_pk_mul_f32 v[94:95], v[100:101], v[94:95]
	v_pk_mul_f32 v[100:101], v[102:103], v[92:93]
	v_cvt_pk_bf16_f32 v90, v96, v97
	v_cvt_pk_bf16_f32 v91, v98, v99
	v_cvt_pk_bf16_f32 v92, v94, v95
	v_cvt_pk_bf16_f32 v93, v100, v101
	global_store_dwordx4 v[106:107], v[90:93], off
	s_add_i32 s10, s1, 4
	s_ashr_i32 s11, s10, 31
	s_lshl_b64 s[10:11], s[10:11], 13
	s_add_u32 s10, s42, s10
	v_pk_mul_f32 v[98:99], v[82:83], v[22:23]
	s_addc_u32 s11, s43, s11
	v_pk_fma_f32 v[98:99], v[74:75], v[14:15], v[98:99]
	v_mov_b32_e32 v74, v82
	v_mov_b32_e32 v75, v83
	v_lshl_add_u64 v[82:83], s[10:11], 0, v[38:39]
	v_pk_mul_f32 v[100:101], v[84:85], v[24:25]
	v_pk_mul_f32 v[102:103], v[86:87], v[18:19]
	v_pk_mul_f32 v[104:105], v[88:89], v[20:21]
	v_add_co_u32_e32 v106, vcc, 0x1000, v82
	v_pk_fma_f32 v[100:101], v[76:77], v[16:17], v[100:101]
	v_pk_fma_f32 v[102:103], v[78:79], v[10:11], v[102:103]
	v_pk_fma_f32 v[104:105], v[80:81], v[12:13], v[104:105]
	v_mov_b32_e32 v76, v84
	v_mov_b32_e32 v77, v85
	v_mov_b32_e32 v78, v86
	v_mov_b32_e32 v79, v87
	v_mov_b32_e32 v80, v88
	v_mov_b32_e32 v81, v89
	v_addc_co_u32_e32 v107, vcc, 0, v83, vcc
	s_waitcnt vmcnt(7)
	v_lshlrev_b32_e32 v82, 16, v148
	v_and_b32_e32 v83, 0xffff0000, v148
	v_lshlrev_b32_e32 v84, 16, v149
	v_and_b32_e32 v85, 0xffff0000, v149
	v_lshlrev_b32_e32 v86, 16, v150
	v_and_b32_e32 v87, 0xffff0000, v150
	v_lshlrev_b32_e32 v88, 16, v151
	v_and_b32_e32 v89, 0xffff0000, v151
	s_waitcnt vmcnt(6)
	v_lshlrev_b32_e32 v108, 16, v152
	v_and_b32_e32 v109, 0xffff0000, v152
	v_lshlrev_b32_e32 v90, 16, v153
	v_and_b32_e32 v91, 0xffff0000, v153
	v_lshlrev_b32_e32 v94, 16, v154
	v_and_b32_e32 v95, 0xffff0000, v154
	v_lshlrev_b32_e32 v92, 16, v155
	v_and_b32_e32 v93, 0xffff0000, v155
	v_pk_fma_f32 v[96:97], v[30:31], v[82:83], v[98:99]
	v_pk_fma_f32 v[98:99], v[32:33], v[84:85], v[100:101]
	v_pk_fma_f32 v[100:101], v[26:27], v[86:87], v[102:103]
	v_pk_fma_f32 v[102:103], v[28:29], v[88:89], v[104:105]
	v_pk_mul_f32 v[96:97], v[96:97], v[108:109]
	v_pk_mul_f32 v[98:99], v[98:99], v[90:91]
	v_pk_mul_f32 v[94:95], v[100:101], v[94:95]
	v_pk_mul_f32 v[100:101], v[102:103], v[92:93]
	v_cvt_pk_bf16_f32 v90, v96, v97
	v_cvt_pk_bf16_f32 v91, v98, v99
	v_cvt_pk_bf16_f32 v92, v94, v95
	v_cvt_pk_bf16_f32 v93, v100, v101
	global_store_dwordx4 v[106:107], v[90:93], off
	s_add_i32 s10, s1, 5
	s_ashr_i32 s11, s10, 31
	s_lshl_b64 s[10:11], s[10:11], 13
	s_add_u32 s10, s42, s10
	v_pk_mul_f32 v[98:99], v[82:83], v[22:23]
	s_addc_u32 s11, s43, s11
	v_pk_fma_f32 v[98:99], v[74:75], v[14:15], v[98:99]
	v_mov_b32_e32 v74, v82
	v_mov_b32_e32 v75, v83
	v_lshl_add_u64 v[82:83], s[10:11], 0, v[38:39]
	v_pk_mul_f32 v[100:101], v[84:85], v[24:25]
	v_pk_mul_f32 v[102:103], v[86:87], v[18:19]
	v_pk_mul_f32 v[104:105], v[88:89], v[20:21]
	v_add_co_u32_e32 v106, vcc, 0x1000, v82
	v_pk_fma_f32 v[100:101], v[76:77], v[16:17], v[100:101]
	v_pk_fma_f32 v[102:103], v[78:79], v[10:11], v[102:103]
	v_pk_fma_f32 v[104:105], v[80:81], v[12:13], v[104:105]
	v_mov_b32_e32 v76, v84
	v_mov_b32_e32 v77, v85
	v_mov_b32_e32 v78, v86
	v_mov_b32_e32 v79, v87
	v_mov_b32_e32 v80, v88
	v_mov_b32_e32 v81, v89
	v_addc_co_u32_e32 v107, vcc, 0, v83, vcc
	s_waitcnt vmcnt(5)
	v_lshlrev_b32_e32 v82, 16, v156
	v_and_b32_e32 v83, 0xffff0000, v156
	v_lshlrev_b32_e32 v84, 16, v157
	v_and_b32_e32 v85, 0xffff0000, v157
	v_lshlrev_b32_e32 v86, 16, v158
	v_and_b32_e32 v87, 0xffff0000, v158
	v_lshlrev_b32_e32 v88, 16, v159
	v_and_b32_e32 v89, 0xffff0000, v159
	s_waitcnt vmcnt(4)
	v_lshlrev_b32_e32 v108, 16, v160
	v_and_b32_e32 v109, 0xffff0000, v160
	v_lshlrev_b32_e32 v90, 16, v161
	v_and_b32_e32 v91, 0xffff0000, v161
	v_lshlrev_b32_e32 v94, 16, v162
	v_and_b32_e32 v95, 0xffff0000, v162
	v_lshlrev_b32_e32 v92, 16, v163
	v_and_b32_e32 v93, 0xffff0000, v163
	v_pk_fma_f32 v[96:97], v[30:31], v[82:83], v[98:99]
	v_pk_fma_f32 v[98:99], v[32:33], v[84:85], v[100:101]
	v_pk_fma_f32 v[100:101], v[26:27], v[86:87], v[102:103]
	v_pk_fma_f32 v[102:103], v[28:29], v[88:89], v[104:105]
	v_pk_mul_f32 v[96:97], v[96:97], v[108:109]
	v_pk_mul_f32 v[98:99], v[98:99], v[90:91]
	v_pk_mul_f32 v[94:95], v[100:101], v[94:95]
	v_pk_mul_f32 v[100:101], v[102:103], v[92:93]
	v_cvt_pk_bf16_f32 v90, v96, v97
	v_cvt_pk_bf16_f32 v91, v98, v99
	v_cvt_pk_bf16_f32 v92, v94, v95
	v_cvt_pk_bf16_f32 v93, v100, v101
	global_store_dwordx4 v[106:107], v[90:93], off
	s_add_i32 s10, s1, 6
	s_ashr_i32 s11, s10, 31
	s_lshl_b64 s[10:11], s[10:11], 13
	s_add_u32 s10, s42, s10
	v_pk_mul_f32 v[98:99], v[82:83], v[22:23]
	s_addc_u32 s11, s43, s11
	v_pk_fma_f32 v[98:99], v[74:75], v[14:15], v[98:99]
	v_mov_b32_e32 v74, v82
	v_mov_b32_e32 v75, v83
	v_lshl_add_u64 v[82:83], s[10:11], 0, v[38:39]
	v_pk_mul_f32 v[100:101], v[84:85], v[24:25]
	v_pk_mul_f32 v[102:103], v[86:87], v[18:19]
	v_pk_mul_f32 v[104:105], v[88:89], v[20:21]
	v_add_co_u32_e32 v106, vcc, 0x1000, v82
	v_pk_fma_f32 v[100:101], v[76:77], v[16:17], v[100:101]
	v_pk_fma_f32 v[102:103], v[78:79], v[10:11], v[102:103]
	v_pk_fma_f32 v[104:105], v[80:81], v[12:13], v[104:105]
	v_mov_b32_e32 v76, v84
	v_mov_b32_e32 v77, v85
	v_mov_b32_e32 v78, v86
	v_mov_b32_e32 v79, v87
	v_mov_b32_e32 v80, v88
	v_mov_b32_e32 v81, v89
	v_addc_co_u32_e32 v107, vcc, 0, v83, vcc
	s_waitcnt vmcnt(3)
	v_lshlrev_b32_e32 v82, 16, v164
	v_and_b32_e32 v83, 0xffff0000, v164
	v_lshlrev_b32_e32 v84, 16, v165
	v_and_b32_e32 v85, 0xffff0000, v165
	v_lshlrev_b32_e32 v86, 16, v166
	v_and_b32_e32 v87, 0xffff0000, v166
	v_lshlrev_b32_e32 v88, 16, v167
	v_and_b32_e32 v89, 0xffff0000, v167
	s_waitcnt vmcnt(2)
	v_lshlrev_b32_e32 v108, 16, v168
	v_and_b32_e32 v109, 0xffff0000, v168
	v_lshlrev_b32_e32 v90, 16, v169
	v_and_b32_e32 v91, 0xffff0000, v169
	v_lshlrev_b32_e32 v94, 16, v170
	v_and_b32_e32 v95, 0xffff0000, v170
	v_lshlrev_b32_e32 v92, 16, v171
	v_and_b32_e32 v93, 0xffff0000, v171
	v_pk_fma_f32 v[96:97], v[30:31], v[82:83], v[98:99]
	v_pk_fma_f32 v[98:99], v[32:33], v[84:85], v[100:101]
	v_pk_fma_f32 v[100:101], v[26:27], v[86:87], v[102:103]
	v_pk_fma_f32 v[102:103], v[28:29], v[88:89], v[104:105]
	v_pk_mul_f32 v[96:97], v[96:97], v[108:109]
	v_pk_mul_f32 v[98:99], v[98:99], v[90:91]
	v_pk_mul_f32 v[94:95], v[100:101], v[94:95]
	v_pk_mul_f32 v[100:101], v[102:103], v[92:93]
	v_cvt_pk_bf16_f32 v90, v96, v97
	v_cvt_pk_bf16_f32 v91, v98, v99
	v_cvt_pk_bf16_f32 v92, v94, v95
	v_cvt_pk_bf16_f32 v93, v100, v101
	global_store_dwordx4 v[106:107], v[90:93], off
	s_add_i32 s10, s1, 7
	s_ashr_i32 s11, s10, 31
	s_lshl_b64 s[10:11], s[10:11], 13
	s_add_u32 s10, s42, s10
	v_pk_mul_f32 v[98:99], v[82:83], v[22:23]
	s_addc_u32 s11, s43, s11
	v_pk_fma_f32 v[98:99], v[74:75], v[14:15], v[98:99]
	v_mov_b32_e32 v74, v82
	v_mov_b32_e32 v75, v83
	v_lshl_add_u64 v[82:83], s[10:11], 0, v[38:39]
	v_pk_mul_f32 v[100:101], v[84:85], v[24:25]
	v_pk_mul_f32 v[102:103], v[86:87], v[18:19]
	v_pk_mul_f32 v[104:105], v[88:89], v[20:21]
	v_add_co_u32_e32 v106, vcc, 0x1000, v82
	v_pk_fma_f32 v[100:101], v[76:77], v[16:17], v[100:101]
	v_pk_fma_f32 v[102:103], v[78:79], v[10:11], v[102:103]
	v_pk_fma_f32 v[104:105], v[80:81], v[12:13], v[104:105]
	v_mov_b32_e32 v76, v84
	v_mov_b32_e32 v77, v85
	v_mov_b32_e32 v78, v86
	v_mov_b32_e32 v79, v87
	v_mov_b32_e32 v80, v88
	v_mov_b32_e32 v81, v89
	v_addc_co_u32_e32 v107, vcc, 0, v83, vcc
	s_waitcnt vmcnt(1)
	v_lshlrev_b32_e32 v82, 16, v172
	v_and_b32_e32 v83, 0xffff0000, v172
	v_lshlrev_b32_e32 v84, 16, v173
	v_and_b32_e32 v85, 0xffff0000, v173
	v_lshlrev_b32_e32 v86, 16, v174
	v_and_b32_e32 v87, 0xffff0000, v174
	v_lshlrev_b32_e32 v88, 16, v175
	v_and_b32_e32 v89, 0xffff0000, v175
	s_waitcnt vmcnt(0)
	v_lshlrev_b32_e32 v108, 16, v176
	v_and_b32_e32 v109, 0xffff0000, v176
	v_lshlrev_b32_e32 v90, 16, v177
	v_and_b32_e32 v91, 0xffff0000, v177
	v_lshlrev_b32_e32 v94, 16, v178
	v_and_b32_e32 v95, 0xffff0000, v178
	v_lshlrev_b32_e32 v92, 16, v179
	v_and_b32_e32 v93, 0xffff0000, v179
	v_pk_fma_f32 v[96:97], v[30:31], v[82:83], v[98:99]
	v_pk_fma_f32 v[98:99], v[32:33], v[84:85], v[100:101]
	v_pk_fma_f32 v[100:101], v[26:27], v[86:87], v[102:103]
	v_pk_fma_f32 v[102:103], v[28:29], v[88:89], v[104:105]
	v_pk_mul_f32 v[96:97], v[96:97], v[108:109]
	v_pk_mul_f32 v[98:99], v[98:99], v[90:91]
	v_pk_mul_f32 v[94:95], v[100:101], v[94:95]
	v_pk_mul_f32 v[100:101], v[102:103], v[92:93]
	v_cvt_pk_bf16_f32 v90, v96, v97
	v_cvt_pk_bf16_f32 v91, v98, v99
	v_cvt_pk_bf16_f32 v92, v94, v95
	v_cvt_pk_bf16_f32 v93, v100, v101
	global_store_dwordx4 v[106:107], v[90:93], off
	s_mov_b32 s12, 8
	global_load_dwordx4 v[10:13], v[50:51], off offset:16
	global_load_dwordx4 v[14:17], v[50:51], off
	global_load_dwordx4 v[18:21], v[52:53], off offset:16
	global_load_dwordx4 v[22:25], v[52:53], off
	global_load_dwordx4 v[26:29], v[54:55], off offset:16
	global_load_dwordx4 v[30:33], v[54:55], off
	s_and_b64 vcc, exec, s[4:5]
	s_cbranch_vccnz .LBB0_430
	global_load_dwordx4 v[78:81], v72, s[6:7] offset:2048
	global_load_dwordx4 v[86:89], v72, s[8:9] offset:2048
	s_waitcnt vmcnt(1)
	v_lshlrev_b32_e32 v74, 16, v78
	v_and_b32_e32 v75, 0xffff0000, v78
	v_lshlrev_b32_e32 v76, 16, v79
	v_and_b32_e32 v77, 0xffff0000, v79
	v_lshlrev_b32_e32 v78, 16, v80
	v_and_b32_e32 v79, 0xffff0000, v80
	v_lshlrev_b32_e32 v80, 16, v81
	v_and_b32_e32 v81, 0xffff0000, v81
	s_waitcnt vmcnt(0)
	v_lshlrev_b32_e32 v82, 16, v86
	v_and_b32_e32 v83, 0xffff0000, v86
	v_lshlrev_b32_e32 v84, 16, v87
	v_and_b32_e32 v85, 0xffff0000, v87
	v_lshlrev_b32_e32 v86, 16, v88
	v_and_b32_e32 v87, 0xffff0000, v88
	v_lshlrev_b32_e32 v88, 16, v89
	v_and_b32_e32 v89, 0xffff0000, v89
	s_branch .LBB0_431

.LBB0_432:
	s_add_i32 s10, s1, 0
	s_ashr_i32 s11, s10, 31
	s_lshl_b64 s[14:15], s[10:11], 12
	v_or_b32_e32 v90, s14, v68
	v_mov_b32_e32 v91, s15
	v_lshl_add_u64 v[92:93], s[44:45], 0, v[90:91]
	v_lshl_add_u64 v[94:95], s[18:19], 0, v[90:91]
	global_load_dwordx4 v[116:119], v[92:93], off
	s_nop 0
	global_load_dwordx4 v[120:123], v[94:95], off
	s_add_i32 s10, s1, 1
	s_ashr_i32 s11, s10, 31
	s_lshl_b64 s[14:15], s[10:11], 12
	v_or_b32_e32 v90, s14, v68
	v_mov_b32_e32 v91, s15
	v_lshl_add_u64 v[92:93], s[44:45], 0, v[90:91]
	v_lshl_add_u64 v[94:95], s[18:19], 0, v[90:91]
	global_load_dwordx4 v[124:127], v[92:93], off
	s_nop 0
	global_load_dwordx4 v[128:131], v[94:95], off
	s_add_i32 s10, s1, 2
	s_ashr_i32 s11, s10, 31
	s_lshl_b64 s[14:15], s[10:11], 12
	v_or_b32_e32 v90, s14, v68
	v_mov_b32_e32 v91, s15
	v_lshl_add_u64 v[92:93], s[44:45], 0, v[90:91]
	v_lshl_add_u64 v[94:95], s[18:19], 0, v[90:91]
	global_load_dwordx4 v[132:135], v[92:93], off
	s_nop 0
	global_load_dwordx4 v[136:139], v[94:95], off
	s_add_i32 s10, s1, 3
	s_ashr_i32 s11, s10, 31
	s_lshl_b64 s[14:15], s[10:11], 12
	v_or_b32_e32 v90, s14, v68
	v_mov_b32_e32 v91, s15
	v_lshl_add_u64 v[92:93], s[44:45], 0, v[90:91]
	v_lshl_add_u64 v[94:95], s[18:19], 0, v[90:91]
	global_load_dwordx4 v[140:143], v[92:93], off
	s_nop 0
	global_load_dwordx4 v[144:147], v[94:95], off
	s_add_i32 s10, s1, 4
	s_ashr_i32 s11, s10, 31
	s_lshl_b64 s[14:15], s[10:11], 12
	v_or_b32_e32 v90, s14, v68
	v_mov_b32_e32 v91, s15
	v_lshl_add_u64 v[92:93], s[44:45], 0, v[90:91]
	v_lshl_add_u64 v[94:95], s[18:19], 0, v[90:91]
	global_load_dwordx4 v[148:151], v[92:93], off
	s_nop 0
	global_load_dwordx4 v[152:155], v[94:95], off
	s_add_i32 s10, s1, 5
	s_ashr_i32 s11, s10, 31
	s_lshl_b64 s[14:15], s[10:11], 12
	v_or_b32_e32 v90, s14, v68
	v_mov_b32_e32 v91, s15
	v_lshl_add_u64 v[92:93], s[44:45], 0, v[90:91]
	v_lshl_add_u64 v[94:95], s[18:19], 0, v[90:91]
	global_load_dwordx4 v[156:159], v[92:93], off
	s_nop 0
	global_load_dwordx4 v[160:163], v[94:95], off
	s_add_i32 s10, s1, 6
	s_ashr_i32 s11, s10, 31
	s_lshl_b64 s[14:15], s[10:11], 12
	v_or_b32_e32 v90, s14, v68
	v_mov_b32_e32 v91, s15
	v_lshl_add_u64 v[92:93], s[44:45], 0, v[90:91]
	v_lshl_add_u64 v[94:95], s[18:19], 0, v[90:91]
	global_load_dwordx4 v[164:167], v[92:93], off
	s_nop 0
	global_load_dwordx4 v[168:171], v[94:95], off
	s_add_i32 s10, s1, 7
	s_ashr_i32 s11, s10, 31
	s_lshl_b64 s[14:15], s[10:11], 12
	v_or_b32_e32 v90, s14, v68
	v_mov_b32_e32 v91, s15
	v_lshl_add_u64 v[92:93], s[44:45], 0, v[90:91]
	v_lshl_add_u64 v[94:95], s[18:19], 0, v[90:91]
	global_load_dwordx4 v[172:175], v[92:93], off
	s_nop 0
	global_load_dwordx4 v[176:179], v[94:95], off
	s_add_i32 s10, s1, 0
	s_ashr_i32 s11, s10, 31
	s_lshl_b64 s[10:11], s[10:11], 13
	s_add_u32 s10, s42, s10
	v_mov_b32_e32 v69, v39
	s_waitcnt vmcnt(18)
	v_pk_mul_f32 v[98:99], v[82:83], v[22:23]
	s_addc_u32 s11, s43, s11
	v_pk_fma_f32 v[98:99], v[74:75], v[14:15], v[98:99]
	v_mov_b32_e32 v74, v82
	v_mov_b32_e32 v75, v83
	v_lshl_add_u64 v[82:83], s[10:11], 0, v[68:69]
	v_pk_mul_f32 v[100:101], v[84:85], v[24:25]
	v_pk_mul_f32 v[102:103], v[86:87], v[18:19]
	v_pk_mul_f32 v[104:105], v[88:89], v[20:21]
	v_add_co_u32_e32 v106, vcc, 0x1000, v82
	v_pk_fma_f32 v[100:101], v[76:77], v[16:17], v[100:101]
	v_pk_fma_f32 v[102:103], v[78:79], v[10:11], v[102:103]
	v_pk_fma_f32 v[104:105], v[80:81], v[12:13], v[104:105]
	v_mov_b32_e32 v76, v84
	v_mov_b32_e32 v77, v85
	v_mov_b32_e32 v78, v86
	v_mov_b32_e32 v79, v87
	v_mov_b32_e32 v80, v88
	v_mov_b32_e32 v81, v89
	v_addc_co_u32_e32 v107, vcc, 0, v83, vcc
	s_waitcnt vmcnt(15)
	v_lshlrev_b32_e32 v82, 16, v116
	v_and_b32_e32 v83, 0xffff0000, v116
	v_lshlrev_b32_e32 v84, 16, v117
	v_and_b32_e32 v85, 0xffff0000, v117
	v_lshlrev_b32_e32 v86, 16, v118
	v_and_b32_e32 v87, 0xffff0000, v118
	v_lshlrev_b32_e32 v88, 16, v119
	v_and_b32_e32 v89, 0xffff0000, v119
	s_waitcnt vmcnt(14)
	v_lshlrev_b32_e32 v108, 16, v120
	v_and_b32_e32 v109, 0xffff0000, v120
	v_lshlrev_b32_e32 v90, 16, v121
	v_and_b32_e32 v91, 0xffff0000, v121
	v_lshlrev_b32_e32 v94, 16, v122
	v_and_b32_e32 v95, 0xffff0000, v122
	v_lshlrev_b32_e32 v92, 16, v123
	v_and_b32_e32 v93, 0xffff0000, v123
	v_pk_fma_f32 v[96:97], v[30:31], v[82:83], v[98:99]
	v_pk_fma_f32 v[98:99], v[32:33], v[84:85], v[100:101]
	v_pk_fma_f32 v[100:101], v[26:27], v[86:87], v[102:103]
	v_pk_fma_f32 v[102:103], v[28:29], v[88:89], v[104:105]
	v_pk_mul_f32 v[96:97], v[96:97], v[108:109]
	v_pk_mul_f32 v[98:99], v[98:99], v[90:91]
	v_pk_mul_f32 v[94:95], v[100:101], v[94:95]
	v_pk_mul_f32 v[100:101], v[102:103], v[92:93]
	v_cvt_pk_bf16_f32 v90, v96, v97
	v_cvt_pk_bf16_f32 v91, v98, v99
	v_cvt_pk_bf16_f32 v92, v94, v95
	v_cvt_pk_bf16_f32 v93, v100, v101
	global_store_dwordx4 v[106:107], v[90:93], off
	s_add_i32 s10, s1, 1
	s_ashr_i32 s11, s10, 31
	s_lshl_b64 s[10:11], s[10:11], 13
	s_add_u32 s10, s42, s10
	v_mov_b32_e32 v69, v39
	v_pk_mul_f32 v[98:99], v[82:83], v[22:23]
	s_addc_u32 s11, s43, s11
	v_pk_fma_f32 v[98:99], v[74:75], v[14:15], v[98:99]
	v_mov_b32_e32 v74, v82
	v_mov_b32_e32 v75, v83
	v_lshl_add_u64 v[82:83], s[10:11], 0, v[68:69]
	v_pk_mul_f32 v[100:101], v[84:85], v[24:25]
	v_pk_mul_f32 v[102:103], v[86:87], v[18:19]
	v_pk_mul_f32 v[104:105], v[88:89], v[20:21]
	v_add_co_u32_e32 v106, vcc, 0x1000, v82
	v_pk_fma_f32 v[100:101], v[76:77], v[16:17], v[100:101]
	v_pk_fma_f32 v[102:103], v[78:79], v[10:11], v[102:103]
	v_pk_fma_f32 v[104:105], v[80:81], v[12:13], v[104:105]
	v_mov_b32_e32 v76, v84
	v_mov_b32_e32 v77, v85
	v_mov_b32_e32 v78, v86
	v_mov_b32_e32 v79, v87
	v_mov_b32_e32 v80, v88
	v_mov_b32_e32 v81, v89
	v_addc_co_u32_e32 v107, vcc, 0, v83, vcc
	s_waitcnt vmcnt(13)
	v_lshlrev_b32_e32 v82, 16, v124
	v_and_b32_e32 v83, 0xffff0000, v124
	v_lshlrev_b32_e32 v84, 16, v125
	v_and_b32_e32 v85, 0xffff0000, v125
	v_lshlrev_b32_e32 v86, 16, v126
	v_and_b32_e32 v87, 0xffff0000, v126
	v_lshlrev_b32_e32 v88, 16, v127
	v_and_b32_e32 v89, 0xffff0000, v127
	s_waitcnt vmcnt(12)
	v_lshlrev_b32_e32 v108, 16, v128
	v_and_b32_e32 v109, 0xffff0000, v128
	v_lshlrev_b32_e32 v90, 16, v129
	v_and_b32_e32 v91, 0xffff0000, v129
	v_lshlrev_b32_e32 v94, 16, v130
	v_and_b32_e32 v95, 0xffff0000, v130
	v_lshlrev_b32_e32 v92, 16, v131
	v_and_b32_e32 v93, 0xffff0000, v131
	v_pk_fma_f32 v[96:97], v[30:31], v[82:83], v[98:99]
	v_pk_fma_f32 v[98:99], v[32:33], v[84:85], v[100:101]
	v_pk_fma_f32 v[100:101], v[26:27], v[86:87], v[102:103]
	v_pk_fma_f32 v[102:103], v[28:29], v[88:89], v[104:105]
	v_pk_mul_f32 v[96:97], v[96:97], v[108:109]
	v_pk_mul_f32 v[98:99], v[98:99], v[90:91]
	v_pk_mul_f32 v[94:95], v[100:101], v[94:95]
	v_pk_mul_f32 v[100:101], v[102:103], v[92:93]
	v_cvt_pk_bf16_f32 v90, v96, v97
	v_cvt_pk_bf16_f32 v91, v98, v99
	v_cvt_pk_bf16_f32 v92, v94, v95
	v_cvt_pk_bf16_f32 v93, v100, v101
	global_store_dwordx4 v[106:107], v[90:93], off
	s_add_i32 s10, s1, 2
	s_ashr_i32 s11, s10, 31
	s_lshl_b64 s[10:11], s[10:11], 13
	s_add_u32 s10, s42, s10
	v_mov_b32_e32 v69, v39
	v_pk_mul_f32 v[98:99], v[82:83], v[22:23]
	s_addc_u32 s11, s43, s11
	v_pk_fma_f32 v[98:99], v[74:75], v[14:15], v[98:99]
	v_mov_b32_e32 v74, v82
	v_mov_b32_e32 v75, v83
	v_lshl_add_u64 v[82:83], s[10:11], 0, v[68:69]
	v_pk_mul_f32 v[100:101], v[84:85], v[24:25]
	v_pk_mul_f32 v[102:103], v[86:87], v[18:19]
	v_pk_mul_f32 v[104:105], v[88:89], v[20:21]
	v_add_co_u32_e32 v106, vcc, 0x1000, v82
	v_pk_fma_f32 v[100:101], v[76:77], v[16:17], v[100:101]
	v_pk_fma_f32 v[102:103], v[78:79], v[10:11], v[102:103]
	v_pk_fma_f32 v[104:105], v[80:81], v[12:13], v[104:105]
	v_mov_b32_e32 v76, v84
	v_mov_b32_e32 v77, v85
	v_mov_b32_e32 v78, v86
	v_mov_b32_e32 v79, v87
	v_mov_b32_e32 v80, v88
	v_mov_b32_e32 v81, v89
	v_addc_co_u32_e32 v107, vcc, 0, v83, vcc
	s_waitcnt vmcnt(11)
	v_lshlrev_b32_e32 v82, 16, v132
	v_and_b32_e32 v83, 0xffff0000, v132
	v_lshlrev_b32_e32 v84, 16, v133
	v_and_b32_e32 v85, 0xffff0000, v133
	v_lshlrev_b32_e32 v86, 16, v134
	v_and_b32_e32 v87, 0xffff0000, v134
	v_lshlrev_b32_e32 v88, 16, v135
	v_and_b32_e32 v89, 0xffff0000, v135
	s_waitcnt vmcnt(10)
	v_lshlrev_b32_e32 v108, 16, v136
	v_and_b32_e32 v109, 0xffff0000, v136
	v_lshlrev_b32_e32 v90, 16, v137
	v_and_b32_e32 v91, 0xffff0000, v137
	v_lshlrev_b32_e32 v94, 16, v138
	v_and_b32_e32 v95, 0xffff0000, v138
	v_lshlrev_b32_e32 v92, 16, v139
	v_and_b32_e32 v93, 0xffff0000, v139
	v_pk_fma_f32 v[96:97], v[30:31], v[82:83], v[98:99]
	v_pk_fma_f32 v[98:99], v[32:33], v[84:85], v[100:101]
	v_pk_fma_f32 v[100:101], v[26:27], v[86:87], v[102:103]
	v_pk_fma_f32 v[102:103], v[28:29], v[88:89], v[104:105]
	v_pk_mul_f32 v[96:97], v[96:97], v[108:109]
	v_pk_mul_f32 v[98:99], v[98:99], v[90:91]
	v_pk_mul_f32 v[94:95], v[100:101], v[94:95]
	v_pk_mul_f32 v[100:101], v[102:103], v[92:93]
	v_cvt_pk_bf16_f32 v90, v96, v97
	v_cvt_pk_bf16_f32 v91, v98, v99
	v_cvt_pk_bf16_f32 v92, v94, v95
	v_cvt_pk_bf16_f32 v93, v100, v101
	global_store_dwordx4 v[106:107], v[90:93], off
	s_add_i32 s10, s1, 3
	s_ashr_i32 s11, s10, 31
	s_lshl_b64 s[10:11], s[10:11], 13
	s_add_u32 s10, s42, s10
	v_mov_b32_e32 v69, v39
	v_pk_mul_f32 v[98:99], v[82:83], v[22:23]
	s_addc_u32 s11, s43, s11
	v_pk_fma_f32 v[98:99], v[74:75], v[14:15], v[98:99]
	v_mov_b32_e32 v74, v82
	v_mov_b32_e32 v75, v83
	v_lshl_add_u64 v[82:83], s[10:11], 0, v[68:69]
	v_pk_mul_f32 v[100:101], v[84:85], v[24:25]
	v_pk_mul_f32 v[102:103], v[86:87], v[18:19]
	v_pk_mul_f32 v[104:105], v[88:89], v[20:21]
	v_add_co_u32_e32 v106, vcc, 0x1000, v82
	v_pk_fma_f32 v[100:101], v[76:77], v[16:17], v[100:101]
	v_pk_fma_f32 v[102:103], v[78:79], v[10:11], v[102:103]
	v_pk_fma_f32 v[104:105], v[80:81], v[12:13], v[104:105]
	v_mov_b32_e32 v76, v84
	v_mov_b32_e32 v77, v85
	v_mov_b32_e32 v78, v86
	v_mov_b32_e32 v79, v87
	v_mov_b32_e32 v80, v88
	v_mov_b32_e32 v81, v89
	v_addc_co_u32_e32 v107, vcc, 0, v83, vcc
	s_waitcnt vmcnt(9)
	v_lshlrev_b32_e32 v82, 16, v140
	v_and_b32_e32 v83, 0xffff0000, v140
	v_lshlrev_b32_e32 v84, 16, v141
	v_and_b32_e32 v85, 0xffff0000, v141
	v_lshlrev_b32_e32 v86, 16, v142
	v_and_b32_e32 v87, 0xffff0000, v142
	v_lshlrev_b32_e32 v88, 16, v143
	v_and_b32_e32 v89, 0xffff0000, v143
	s_waitcnt vmcnt(8)
	v_lshlrev_b32_e32 v108, 16, v144
	v_and_b32_e32 v109, 0xffff0000, v144
	v_lshlrev_b32_e32 v90, 16, v145
	v_and_b32_e32 v91, 0xffff0000, v145
	v_lshlrev_b32_e32 v94, 16, v146
	v_and_b32_e32 v95, 0xffff0000, v146
	v_lshlrev_b32_e32 v92, 16, v147
	v_and_b32_e32 v93, 0xffff0000, v147
	v_pk_fma_f32 v[96:97], v[30:31], v[82:83], v[98:99]
	v_pk_fma_f32 v[98:99], v[32:33], v[84:85], v[100:101]
	v_pk_fma_f32 v[100:101], v[26:27], v[86:87], v[102:103]
	v_pk_fma_f32 v[102:103], v[28:29], v[88:89], v[104:105]
	v_pk_mul_f32 v[96:97], v[96:97], v[108:109]
	v_pk_mul_f32 v[98:99], v[98:99], v[90:91]
	v_pk_mul_f32 v[94:95], v[100:101], v[94:95]
	v_pk_mul_f32 v[100:101], v[102:103], v[92:93]
	v_cvt_pk_bf16_f32 v90, v96, v97
	v_cvt_pk_bf16_f32 v91, v98, v99
	v_cvt_pk_bf16_f32 v92, v94, v95
	v_cvt_pk_bf16_f32 v93, v100, v101
	global_store_dwordx4 v[106:107], v[90:93], off
	s_add_i32 s10, s1, 4
	s_ashr_i32 s11, s10, 31
	s_lshl_b64 s[10:11], s[10:11], 13
	s_add_u32 s10, s42, s10
	v_mov_b32_e32 v69, v39
	v_pk_mul_f32 v[98:99], v[82:83], v[22:23]
	s_addc_u32 s11, s43, s11
	v_pk_fma_f32 v[98:99], v[74:75], v[14:15], v[98:99]
	v_mov_b32_e32 v74, v82
	v_mov_b32_e32 v75, v83
	v_lshl_add_u64 v[82:83], s[10:11], 0, v[68:69]
	v_pk_mul_f32 v[100:101], v[84:85], v[24:25]
	v_pk_mul_f32 v[102:103], v[86:87], v[18:19]
	v_pk_mul_f32 v[104:105], v[88:89], v[20:21]
	v_add_co_u32_e32 v106, vcc, 0x1000, v82
	v_pk_fma_f32 v[100:101], v[76:77], v[16:17], v[100:101]
	v_pk_fma_f32 v[102:103], v[78:79], v[10:11], v[102:103]
	v_pk_fma_f32 v[104:105], v[80:81], v[12:13], v[104:105]
	v_mov_b32_e32 v76, v84
	v_mov_b32_e32 v77, v85
	v_mov_b32_e32 v78, v86
	v_mov_b32_e32 v79, v87
	v_mov_b32_e32 v80, v88
	v_mov_b32_e32 v81, v89
	v_addc_co_u32_e32 v107, vcc, 0, v83, vcc
	s_waitcnt vmcnt(7)
	v_lshlrev_b32_e32 v82, 16, v148
	v_and_b32_e32 v83, 0xffff0000, v148
	v_lshlrev_b32_e32 v84, 16, v149
	v_and_b32_e32 v85, 0xffff0000, v149
	v_lshlrev_b32_e32 v86, 16, v150
	v_and_b32_e32 v87, 0xffff0000, v150
	v_lshlrev_b32_e32 v88, 16, v151
	v_and_b32_e32 v89, 0xffff0000, v151
	s_waitcnt vmcnt(6)
	v_lshlrev_b32_e32 v108, 16, v152
	v_and_b32_e32 v109, 0xffff0000, v152
	v_lshlrev_b32_e32 v90, 16, v153
	v_and_b32_e32 v91, 0xffff0000, v153
	v_lshlrev_b32_e32 v94, 16, v154
	v_and_b32_e32 v95, 0xffff0000, v154
	v_lshlrev_b32_e32 v92, 16, v155
	v_and_b32_e32 v93, 0xffff0000, v155
	v_pk_fma_f32 v[96:97], v[30:31], v[82:83], v[98:99]
	v_pk_fma_f32 v[98:99], v[32:33], v[84:85], v[100:101]
	v_pk_fma_f32 v[100:101], v[26:27], v[86:87], v[102:103]
	v_pk_fma_f32 v[102:103], v[28:29], v[88:89], v[104:105]
	v_pk_mul_f32 v[96:97], v[96:97], v[108:109]
	v_pk_mul_f32 v[98:99], v[98:99], v[90:91]
	v_pk_mul_f32 v[94:95], v[100:101], v[94:95]
	v_pk_mul_f32 v[100:101], v[102:103], v[92:93]
	v_cvt_pk_bf16_f32 v90, v96, v97
	v_cvt_pk_bf16_f32 v91, v98, v99
	v_cvt_pk_bf16_f32 v92, v94, v95
	v_cvt_pk_bf16_f32 v93, v100, v101
	global_store_dwordx4 v[106:107], v[90:93], off
	s_add_i32 s10, s1, 5
	s_ashr_i32 s11, s10, 31
	s_lshl_b64 s[10:11], s[10:11], 13
	s_add_u32 s10, s42, s10
	v_mov_b32_e32 v69, v39
	v_pk_mul_f32 v[98:99], v[82:83], v[22:23]
	s_addc_u32 s11, s43, s11
	v_pk_fma_f32 v[98:99], v[74:75], v[14:15], v[98:99]
	v_mov_b32_e32 v74, v82
	v_mov_b32_e32 v75, v83
	v_lshl_add_u64 v[82:83], s[10:11], 0, v[68:69]
	v_pk_mul_f32 v[100:101], v[84:85], v[24:25]
	v_pk_mul_f32 v[102:103], v[86:87], v[18:19]
	v_pk_mul_f32 v[104:105], v[88:89], v[20:21]
	v_add_co_u32_e32 v106, vcc, 0x1000, v82
	v_pk_fma_f32 v[100:101], v[76:77], v[16:17], v[100:101]
	v_pk_fma_f32 v[102:103], v[78:79], v[10:11], v[102:103]
	v_pk_fma_f32 v[104:105], v[80:81], v[12:13], v[104:105]
	v_mov_b32_e32 v76, v84
	v_mov_b32_e32 v77, v85
	v_mov_b32_e32 v78, v86
	v_mov_b32_e32 v79, v87
	v_mov_b32_e32 v80, v88
	v_mov_b32_e32 v81, v89
	v_addc_co_u32_e32 v107, vcc, 0, v83, vcc
	s_waitcnt vmcnt(5)
	v_lshlrev_b32_e32 v82, 16, v156
	v_and_b32_e32 v83, 0xffff0000, v156
	v_lshlrev_b32_e32 v84, 16, v157
	v_and_b32_e32 v85, 0xffff0000, v157
	v_lshlrev_b32_e32 v86, 16, v158
	v_and_b32_e32 v87, 0xffff0000, v158
	v_lshlrev_b32_e32 v88, 16, v159
	v_and_b32_e32 v89, 0xffff0000, v159
	s_waitcnt vmcnt(4)
	v_lshlrev_b32_e32 v108, 16, v160
	v_and_b32_e32 v109, 0xffff0000, v160
	v_lshlrev_b32_e32 v90, 16, v161
	v_and_b32_e32 v91, 0xffff0000, v161
	v_lshlrev_b32_e32 v94, 16, v162
	v_and_b32_e32 v95, 0xffff0000, v162
	v_lshlrev_b32_e32 v92, 16, v163
	v_and_b32_e32 v93, 0xffff0000, v163
	v_pk_fma_f32 v[96:97], v[30:31], v[82:83], v[98:99]
	v_pk_fma_f32 v[98:99], v[32:33], v[84:85], v[100:101]
	v_pk_fma_f32 v[100:101], v[26:27], v[86:87], v[102:103]
	v_pk_fma_f32 v[102:103], v[28:29], v[88:89], v[104:105]
	v_pk_mul_f32 v[96:97], v[96:97], v[108:109]
	v_pk_mul_f32 v[98:99], v[98:99], v[90:91]
	v_pk_mul_f32 v[94:95], v[100:101], v[94:95]
	v_pk_mul_f32 v[100:101], v[102:103], v[92:93]
	v_cvt_pk_bf16_f32 v90, v96, v97
	v_cvt_pk_bf16_f32 v91, v98, v99
	v_cvt_pk_bf16_f32 v92, v94, v95
	v_cvt_pk_bf16_f32 v93, v100, v101
	global_store_dwordx4 v[106:107], v[90:93], off
	s_add_i32 s10, s1, 6
	s_ashr_i32 s11, s10, 31
	s_lshl_b64 s[10:11], s[10:11], 13
	s_add_u32 s10, s42, s10
	v_mov_b32_e32 v69, v39
	v_pk_mul_f32 v[98:99], v[82:83], v[22:23]
	s_addc_u32 s11, s43, s11
	v_pk_fma_f32 v[98:99], v[74:75], v[14:15], v[98:99]
	v_mov_b32_e32 v74, v82
	v_mov_b32_e32 v75, v83
	v_lshl_add_u64 v[82:83], s[10:11], 0, v[68:69]
	v_pk_mul_f32 v[100:101], v[84:85], v[24:25]
	v_pk_mul_f32 v[102:103], v[86:87], v[18:19]
	v_pk_mul_f32 v[104:105], v[88:89], v[20:21]
	v_add_co_u32_e32 v106, vcc, 0x1000, v82
	v_pk_fma_f32 v[100:101], v[76:77], v[16:17], v[100:101]
	v_pk_fma_f32 v[102:103], v[78:79], v[10:11], v[102:103]
	v_pk_fma_f32 v[104:105], v[80:81], v[12:13], v[104:105]
	v_mov_b32_e32 v76, v84
	v_mov_b32_e32 v77, v85
	v_mov_b32_e32 v78, v86
	v_mov_b32_e32 v79, v87
	v_mov_b32_e32 v80, v88
	v_mov_b32_e32 v81, v89
	v_addc_co_u32_e32 v107, vcc, 0, v83, vcc
	s_waitcnt vmcnt(3)
	v_lshlrev_b32_e32 v82, 16, v164
	v_and_b32_e32 v83, 0xffff0000, v164
	v_lshlrev_b32_e32 v84, 16, v165
	v_and_b32_e32 v85, 0xffff0000, v165
	v_lshlrev_b32_e32 v86, 16, v166
	v_and_b32_e32 v87, 0xffff0000, v166
	v_lshlrev_b32_e32 v88, 16, v167
	v_and_b32_e32 v89, 0xffff0000, v167
	s_waitcnt vmcnt(2)
	v_lshlrev_b32_e32 v108, 16, v168
	v_and_b32_e32 v109, 0xffff0000, v168
	v_lshlrev_b32_e32 v90, 16, v169
	v_and_b32_e32 v91, 0xffff0000, v169
	v_lshlrev_b32_e32 v94, 16, v170
	v_and_b32_e32 v95, 0xffff0000, v170
	v_lshlrev_b32_e32 v92, 16, v171
	v_and_b32_e32 v93, 0xffff0000, v171
	v_pk_fma_f32 v[96:97], v[30:31], v[82:83], v[98:99]
	v_pk_fma_f32 v[98:99], v[32:33], v[84:85], v[100:101]
	v_pk_fma_f32 v[100:101], v[26:27], v[86:87], v[102:103]
	v_pk_fma_f32 v[102:103], v[28:29], v[88:89], v[104:105]
	v_pk_mul_f32 v[96:97], v[96:97], v[108:109]
	v_pk_mul_f32 v[98:99], v[98:99], v[90:91]
	v_pk_mul_f32 v[94:95], v[100:101], v[94:95]
	v_pk_mul_f32 v[100:101], v[102:103], v[92:93]
	v_cvt_pk_bf16_f32 v90, v96, v97
	v_cvt_pk_bf16_f32 v91, v98, v99
	v_cvt_pk_bf16_f32 v92, v94, v95
	v_cvt_pk_bf16_f32 v93, v100, v101
	global_store_dwordx4 v[106:107], v[90:93], off
	s_add_i32 s10, s1, 7
	s_ashr_i32 s11, s10, 31
	s_lshl_b64 s[10:11], s[10:11], 13
	s_add_u32 s10, s42, s10
	v_mov_b32_e32 v69, v39
	v_pk_mul_f32 v[98:99], v[82:83], v[22:23]
	s_addc_u32 s11, s43, s11
	v_pk_fma_f32 v[98:99], v[74:75], v[14:15], v[98:99]
	v_mov_b32_e32 v74, v82
	v_mov_b32_e32 v75, v83
	v_lshl_add_u64 v[82:83], s[10:11], 0, v[68:69]
	v_pk_mul_f32 v[100:101], v[84:85], v[24:25]
	v_pk_mul_f32 v[102:103], v[86:87], v[18:19]
	v_pk_mul_f32 v[104:105], v[88:89], v[20:21]
	v_add_co_u32_e32 v106, vcc, 0x1000, v82
	v_pk_fma_f32 v[100:101], v[76:77], v[16:17], v[100:101]
	v_pk_fma_f32 v[102:103], v[78:79], v[10:11], v[102:103]
	v_pk_fma_f32 v[104:105], v[80:81], v[12:13], v[104:105]
	v_mov_b32_e32 v76, v84
	v_mov_b32_e32 v77, v85
	v_mov_b32_e32 v78, v86
	v_mov_b32_e32 v79, v87
	v_mov_b32_e32 v80, v88
	v_mov_b32_e32 v81, v89
	v_addc_co_u32_e32 v107, vcc, 0, v83, vcc
	s_waitcnt vmcnt(1)
	v_lshlrev_b32_e32 v82, 16, v172
	v_and_b32_e32 v83, 0xffff0000, v172
	v_lshlrev_b32_e32 v84, 16, v173
	v_and_b32_e32 v85, 0xffff0000, v173
	v_lshlrev_b32_e32 v86, 16, v174
	v_and_b32_e32 v87, 0xffff0000, v174
	v_lshlrev_b32_e32 v88, 16, v175
	v_and_b32_e32 v89, 0xffff0000, v175
	s_waitcnt vmcnt(0)
	v_lshlrev_b32_e32 v108, 16, v176
	v_and_b32_e32 v109, 0xffff0000, v176
	v_lshlrev_b32_e32 v90, 16, v177
	v_and_b32_e32 v91, 0xffff0000, v177
	v_lshlrev_b32_e32 v94, 16, v178
	v_and_b32_e32 v95, 0xffff0000, v178
	v_lshlrev_b32_e32 v92, 16, v179
	v_and_b32_e32 v93, 0xffff0000, v179
	v_pk_fma_f32 v[96:97], v[30:31], v[82:83], v[98:99]
	v_pk_fma_f32 v[98:99], v[32:33], v[84:85], v[100:101]
	v_pk_fma_f32 v[100:101], v[26:27], v[86:87], v[102:103]
	v_pk_fma_f32 v[102:103], v[28:29], v[88:89], v[104:105]
	v_pk_mul_f32 v[96:97], v[96:97], v[108:109]
	v_pk_mul_f32 v[98:99], v[98:99], v[90:91]
	v_pk_mul_f32 v[94:95], v[100:101], v[94:95]
	v_pk_mul_f32 v[100:101], v[102:103], v[92:93]
	v_cvt_pk_bf16_f32 v90, v96, v97
	v_cvt_pk_bf16_f32 v91, v98, v99
	v_cvt_pk_bf16_f32 v92, v94, v95
	v_cvt_pk_bf16_f32 v93, v100, v101
	global_store_dwordx4 v[106:107], v[90:93], off
	s_mov_b32 s12, 8
	global_load_dwordx4 v[10:13], v[56:57], off offset:16
	global_load_dwordx4 v[14:17], v[56:57], off
	global_load_dwordx4 v[18:21], v[58:59], off offset:16
	global_load_dwordx4 v[22:25], v[58:59], off
	global_load_dwordx4 v[26:29], v[60:61], off offset:16
	global_load_dwordx4 v[30:33], v[60:61], off
	s_and_b64 vcc, exec, s[4:5]
	s_cbranch_vccnz .LBB0_435
	global_load_dwordx4 v[76:79], v72, s[6:7] offset:3072
	global_load_dwordx4 v[84:87], v72, s[8:9] offset:3072
	s_waitcnt vmcnt(1)
	v_lshlrev_b32_e32 v72, 16, v76
	v_and_b32_e32 v73, 0xffff0000, v76
	v_lshlrev_b32_e32 v74, 16, v77
	v_and_b32_e32 v75, 0xffff0000, v77
	v_lshlrev_b32_e32 v76, 16, v78
	v_and_b32_e32 v77, 0xffff0000, v78
	v_lshlrev_b32_e32 v78, 16, v79
	v_and_b32_e32 v79, 0xffff0000, v79
	s_waitcnt vmcnt(0)
	v_lshlrev_b32_e32 v80, 16, v84
	v_and_b32_e32 v81, 0xffff0000, v84
	v_lshlrev_b32_e32 v82, 16, v85
	v_and_b32_e32 v83, 0xffff0000, v85
	v_lshlrev_b32_e32 v84, 16, v86
	v_and_b32_e32 v85, 0xffff0000, v86
	v_lshlrev_b32_e32 v86, 16, v87
	v_and_b32_e32 v87, 0xffff0000, v87
	s_branch .LBB0_436

.LBB0_437:
	s_add_i32 s4, s1, 0
	s_ashr_i32 s5, s4, 31
	s_lshl_b64 s[8:9], s[4:5], 12
	v_or_b32_e32 v88, s8, v70
	v_mov_b32_e32 v89, s9
	v_lshl_add_u64 v[96:97], s[44:45], 0, v[88:89]
	v_lshl_add_u64 v[98:99], s[18:19], 0, v[88:89]
	global_load_dwordx4 v[116:119], v[96:97], off
	global_load_dwordx4 v[120:123], v[98:99], off
	s_add_i32 s4, s1, 1
	s_ashr_i32 s5, s4, 31
	s_lshl_b64 s[8:9], s[4:5], 12
	v_or_b32_e32 v88, s8, v70
	v_mov_b32_e32 v89, s9
	v_lshl_add_u64 v[96:97], s[44:45], 0, v[88:89]
	v_lshl_add_u64 v[98:99], s[18:19], 0, v[88:89]
	global_load_dwordx4 v[124:127], v[96:97], off
	global_load_dwordx4 v[128:131], v[98:99], off
	s_add_i32 s4, s1, 2
	s_ashr_i32 s5, s4, 31
	s_lshl_b64 s[8:9], s[4:5], 12
	v_or_b32_e32 v88, s8, v70
	v_mov_b32_e32 v89, s9
	v_lshl_add_u64 v[96:97], s[44:45], 0, v[88:89]
	v_lshl_add_u64 v[98:99], s[18:19], 0, v[88:89]
	global_load_dwordx4 v[132:135], v[96:97], off
	global_load_dwordx4 v[136:139], v[98:99], off
	s_add_i32 s4, s1, 3
	s_ashr_i32 s5, s4, 31
	s_lshl_b64 s[8:9], s[4:5], 12
	v_or_b32_e32 v88, s8, v70
	v_mov_b32_e32 v89, s9
	v_lshl_add_u64 v[96:97], s[44:45], 0, v[88:89]
	v_lshl_add_u64 v[98:99], s[18:19], 0, v[88:89]
	global_load_dwordx4 v[140:143], v[96:97], off
	global_load_dwordx4 v[144:147], v[98:99], off
	s_add_i32 s4, s1, 4
	s_ashr_i32 s5, s4, 31
	s_lshl_b64 s[8:9], s[4:5], 12
	v_or_b32_e32 v88, s8, v70
	v_mov_b32_e32 v89, s9
	v_lshl_add_u64 v[96:97], s[44:45], 0, v[88:89]
	v_lshl_add_u64 v[98:99], s[18:19], 0, v[88:89]
	global_load_dwordx4 v[148:151], v[96:97], off
	global_load_dwordx4 v[152:155], v[98:99], off
	s_add_i32 s4, s1, 5
	s_ashr_i32 s5, s4, 31
	s_lshl_b64 s[8:9], s[4:5], 12
	v_or_b32_e32 v88, s8, v70
	v_mov_b32_e32 v89, s9
	v_lshl_add_u64 v[96:97], s[44:45], 0, v[88:89]
	v_lshl_add_u64 v[98:99], s[18:19], 0, v[88:89]
	global_load_dwordx4 v[156:159], v[96:97], off
	global_load_dwordx4 v[160:163], v[98:99], off
	s_add_i32 s4, s1, 6
	s_ashr_i32 s5, s4, 31
	s_lshl_b64 s[8:9], s[4:5], 12
	v_or_b32_e32 v88, s8, v70
	v_mov_b32_e32 v89, s9
	v_lshl_add_u64 v[96:97], s[44:45], 0, v[88:89]
	v_lshl_add_u64 v[98:99], s[18:19], 0, v[88:89]
	global_load_dwordx4 v[164:167], v[96:97], off
	global_load_dwordx4 v[168:171], v[98:99], off
	s_add_i32 s4, s1, 7
	s_ashr_i32 s5, s4, 31
	s_lshl_b64 s[8:9], s[4:5], 12
	v_or_b32_e32 v88, s8, v70
	v_mov_b32_e32 v89, s9
	v_lshl_add_u64 v[96:97], s[44:45], 0, v[88:89]
	v_lshl_add_u64 v[98:99], s[18:19], 0, v[88:89]
	global_load_dwordx4 v[172:175], v[96:97], off
	global_load_dwordx4 v[176:179], v[98:99], off
	s_add_i32 s4, s1, 0
	s_ashr_i32 s5, s4, 31
	s_lshl_b64 s[4:5], s[4:5], 13
	s_add_u32 s4, s42, s4
	v_mov_b32_e32 v71, v39
	s_waitcnt vmcnt(18)
	v_pk_mul_f32 v[96:97], v[80:81], v[22:23]
	s_addc_u32 s5, s43, s5
	v_pk_fma_f32 v[96:97], v[72:73], v[14:15], v[96:97]
	v_mov_b32_e32 v72, v80
	v_mov_b32_e32 v73, v81
	v_lshl_add_u64 v[80:81], s[4:5], 0, v[70:71]
	v_pk_mul_f32 v[98:99], v[82:83], v[24:25]
	v_pk_mul_f32 v[100:101], v[84:85], v[18:19]
	v_pk_mul_f32 v[102:103], v[86:87], v[20:21]
	v_add_co_u32_e32 v104, vcc, 0x1000, v80
	v_pk_fma_f32 v[98:99], v[74:75], v[16:17], v[98:99]
	v_pk_fma_f32 v[100:101], v[76:77], v[10:11], v[100:101]
	v_pk_fma_f32 v[102:103], v[78:79], v[12:13], v[102:103]
	v_mov_b32_e32 v74, v82
	v_mov_b32_e32 v75, v83
	v_mov_b32_e32 v76, v84
	v_mov_b32_e32 v77, v85
	v_mov_b32_e32 v78, v86
	v_mov_b32_e32 v79, v87
	v_addc_co_u32_e32 v105, vcc, 0, v81, vcc
	s_waitcnt vmcnt(15)
	v_lshlrev_b32_e32 v80, 16, v116
	v_and_b32_e32 v81, 0xffff0000, v116
	v_lshlrev_b32_e32 v82, 16, v117
	v_and_b32_e32 v83, 0xffff0000, v117
	v_lshlrev_b32_e32 v84, 16, v118
	v_and_b32_e32 v85, 0xffff0000, v118
	v_lshlrev_b32_e32 v86, 16, v119
	v_and_b32_e32 v87, 0xffff0000, v119
	s_waitcnt vmcnt(14)
	v_lshlrev_b32_e32 v106, 16, v120
	v_and_b32_e32 v107, 0xffff0000, v120
	v_lshlrev_b32_e32 v88, 16, v121
	v_and_b32_e32 v89, 0xffff0000, v121
	v_lshlrev_b32_e32 v92, 16, v122
	v_and_b32_e32 v93, 0xffff0000, v122
	v_lshlrev_b32_e32 v90, 16, v123
	v_and_b32_e32 v91, 0xffff0000, v123
	v_pk_fma_f32 v[94:95], v[30:31], v[80:81], v[96:97]
	v_pk_fma_f32 v[96:97], v[32:33], v[82:83], v[98:99]
	v_pk_fma_f32 v[98:99], v[26:27], v[84:85], v[100:101]
	v_pk_fma_f32 v[100:101], v[28:29], v[86:87], v[102:103]
	v_pk_mul_f32 v[94:95], v[94:95], v[106:107]
	v_pk_mul_f32 v[96:97], v[96:97], v[88:89]
	v_pk_mul_f32 v[92:93], v[98:99], v[92:93]
	v_pk_mul_f32 v[98:99], v[100:101], v[90:91]
	v_cvt_pk_bf16_f32 v88, v94, v95
	v_cvt_pk_bf16_f32 v89, v96, v97
	v_cvt_pk_bf16_f32 v90, v92, v93
	v_cvt_pk_bf16_f32 v91, v98, v99
	global_store_dwordx4 v[104:105], v[88:91], off
	s_add_i32 s4, s1, 1
	s_ashr_i32 s5, s4, 31
	s_lshl_b64 s[4:5], s[4:5], 13
	s_add_u32 s4, s42, s4
	v_mov_b32_e32 v71, v39
	v_pk_mul_f32 v[96:97], v[80:81], v[22:23]
	s_addc_u32 s5, s43, s5
	v_pk_fma_f32 v[96:97], v[72:73], v[14:15], v[96:97]
	v_mov_b32_e32 v72, v80
	v_mov_b32_e32 v73, v81
	v_lshl_add_u64 v[80:81], s[4:5], 0, v[70:71]
	v_pk_mul_f32 v[98:99], v[82:83], v[24:25]
	v_pk_mul_f32 v[100:101], v[84:85], v[18:19]
	v_pk_mul_f32 v[102:103], v[86:87], v[20:21]
	v_add_co_u32_e32 v104, vcc, 0x1000, v80
	v_pk_fma_f32 v[98:99], v[74:75], v[16:17], v[98:99]
	v_pk_fma_f32 v[100:101], v[76:77], v[10:11], v[100:101]
	v_pk_fma_f32 v[102:103], v[78:79], v[12:13], v[102:103]
	v_mov_b32_e32 v74, v82
	v_mov_b32_e32 v75, v83
	v_mov_b32_e32 v76, v84
	v_mov_b32_e32 v77, v85
	v_mov_b32_e32 v78, v86
	v_mov_b32_e32 v79, v87
	v_addc_co_u32_e32 v105, vcc, 0, v81, vcc
	s_waitcnt vmcnt(13)
	v_lshlrev_b32_e32 v80, 16, v124
	v_and_b32_e32 v81, 0xffff0000, v124
	v_lshlrev_b32_e32 v82, 16, v125
	v_and_b32_e32 v83, 0xffff0000, v125
	v_lshlrev_b32_e32 v84, 16, v126
	v_and_b32_e32 v85, 0xffff0000, v126
	v_lshlrev_b32_e32 v86, 16, v127
	v_and_b32_e32 v87, 0xffff0000, v127
	s_waitcnt vmcnt(12)
	v_lshlrev_b32_e32 v106, 16, v128
	v_and_b32_e32 v107, 0xffff0000, v128
	v_lshlrev_b32_e32 v88, 16, v129
	v_and_b32_e32 v89, 0xffff0000, v129
	v_lshlrev_b32_e32 v92, 16, v130
	v_and_b32_e32 v93, 0xffff0000, v130
	v_lshlrev_b32_e32 v90, 16, v131
	v_and_b32_e32 v91, 0xffff0000, v131
	v_pk_fma_f32 v[94:95], v[30:31], v[80:81], v[96:97]
	v_pk_fma_f32 v[96:97], v[32:33], v[82:83], v[98:99]
	v_pk_fma_f32 v[98:99], v[26:27], v[84:85], v[100:101]
	v_pk_fma_f32 v[100:101], v[28:29], v[86:87], v[102:103]
	v_pk_mul_f32 v[94:95], v[94:95], v[106:107]
	v_pk_mul_f32 v[96:97], v[96:97], v[88:89]
	v_pk_mul_f32 v[92:93], v[98:99], v[92:93]
	v_pk_mul_f32 v[98:99], v[100:101], v[90:91]
	v_cvt_pk_bf16_f32 v88, v94, v95
	v_cvt_pk_bf16_f32 v89, v96, v97
	v_cvt_pk_bf16_f32 v90, v92, v93
	v_cvt_pk_bf16_f32 v91, v98, v99
	global_store_dwordx4 v[104:105], v[88:91], off
	s_add_i32 s4, s1, 2
	s_ashr_i32 s5, s4, 31
	s_lshl_b64 s[4:5], s[4:5], 13
	s_add_u32 s4, s42, s4
	v_mov_b32_e32 v71, v39
	v_pk_mul_f32 v[96:97], v[80:81], v[22:23]
	s_addc_u32 s5, s43, s5
	v_pk_fma_f32 v[96:97], v[72:73], v[14:15], v[96:97]
	v_mov_b32_e32 v72, v80
	v_mov_b32_e32 v73, v81
	v_lshl_add_u64 v[80:81], s[4:5], 0, v[70:71]
	v_pk_mul_f32 v[98:99], v[82:83], v[24:25]
	v_pk_mul_f32 v[100:101], v[84:85], v[18:19]
	v_pk_mul_f32 v[102:103], v[86:87], v[20:21]
	v_add_co_u32_e32 v104, vcc, 0x1000, v80
	v_pk_fma_f32 v[98:99], v[74:75], v[16:17], v[98:99]
	v_pk_fma_f32 v[100:101], v[76:77], v[10:11], v[100:101]
	v_pk_fma_f32 v[102:103], v[78:79], v[12:13], v[102:103]
	v_mov_b32_e32 v74, v82
	v_mov_b32_e32 v75, v83
	v_mov_b32_e32 v76, v84
	v_mov_b32_e32 v77, v85
	v_mov_b32_e32 v78, v86
	v_mov_b32_e32 v79, v87
	v_addc_co_u32_e32 v105, vcc, 0, v81, vcc
	s_waitcnt vmcnt(11)
	v_lshlrev_b32_e32 v80, 16, v132
	v_and_b32_e32 v81, 0xffff0000, v132
	v_lshlrev_b32_e32 v82, 16, v133
	v_and_b32_e32 v83, 0xffff0000, v133
	v_lshlrev_b32_e32 v84, 16, v134
	v_and_b32_e32 v85, 0xffff0000, v134
	v_lshlrev_b32_e32 v86, 16, v135
	v_and_b32_e32 v87, 0xffff0000, v135
	s_waitcnt vmcnt(10)
	v_lshlrev_b32_e32 v106, 16, v136
	v_and_b32_e32 v107, 0xffff0000, v136
	v_lshlrev_b32_e32 v88, 16, v137
	v_and_b32_e32 v89, 0xffff0000, v137
	v_lshlrev_b32_e32 v92, 16, v138
	v_and_b32_e32 v93, 0xffff0000, v138
	v_lshlrev_b32_e32 v90, 16, v139
	v_and_b32_e32 v91, 0xffff0000, v139
	v_pk_fma_f32 v[94:95], v[30:31], v[80:81], v[96:97]
	v_pk_fma_f32 v[96:97], v[32:33], v[82:83], v[98:99]
	v_pk_fma_f32 v[98:99], v[26:27], v[84:85], v[100:101]
	v_pk_fma_f32 v[100:101], v[28:29], v[86:87], v[102:103]
	v_pk_mul_f32 v[94:95], v[94:95], v[106:107]
	v_pk_mul_f32 v[96:97], v[96:97], v[88:89]
	v_pk_mul_f32 v[92:93], v[98:99], v[92:93]
	v_pk_mul_f32 v[98:99], v[100:101], v[90:91]
	v_cvt_pk_bf16_f32 v88, v94, v95
	v_cvt_pk_bf16_f32 v89, v96, v97
	v_cvt_pk_bf16_f32 v90, v92, v93
	v_cvt_pk_bf16_f32 v91, v98, v99
	global_store_dwordx4 v[104:105], v[88:91], off
	s_add_i32 s4, s1, 3
	s_ashr_i32 s5, s4, 31
	s_lshl_b64 s[4:5], s[4:5], 13
	s_add_u32 s4, s42, s4
	v_mov_b32_e32 v71, v39
	v_pk_mul_f32 v[96:97], v[80:81], v[22:23]
	s_addc_u32 s5, s43, s5
	v_pk_fma_f32 v[96:97], v[72:73], v[14:15], v[96:97]
	v_mov_b32_e32 v72, v80
	v_mov_b32_e32 v73, v81
	v_lshl_add_u64 v[80:81], s[4:5], 0, v[70:71]
	v_pk_mul_f32 v[98:99], v[82:83], v[24:25]
	v_pk_mul_f32 v[100:101], v[84:85], v[18:19]
	v_pk_mul_f32 v[102:103], v[86:87], v[20:21]
	v_add_co_u32_e32 v104, vcc, 0x1000, v80
	v_pk_fma_f32 v[98:99], v[74:75], v[16:17], v[98:99]
	v_pk_fma_f32 v[100:101], v[76:77], v[10:11], v[100:101]
	v_pk_fma_f32 v[102:103], v[78:79], v[12:13], v[102:103]
	v_mov_b32_e32 v74, v82
	v_mov_b32_e32 v75, v83
	v_mov_b32_e32 v76, v84
	v_mov_b32_e32 v77, v85
	v_mov_b32_e32 v78, v86
	v_mov_b32_e32 v79, v87
	v_addc_co_u32_e32 v105, vcc, 0, v81, vcc
	s_waitcnt vmcnt(9)
	v_lshlrev_b32_e32 v80, 16, v140
	v_and_b32_e32 v81, 0xffff0000, v140
	v_lshlrev_b32_e32 v82, 16, v141
	v_and_b32_e32 v83, 0xffff0000, v141
	v_lshlrev_b32_e32 v84, 16, v142
	v_and_b32_e32 v85, 0xffff0000, v142
	v_lshlrev_b32_e32 v86, 16, v143
	v_and_b32_e32 v87, 0xffff0000, v143
	s_waitcnt vmcnt(8)
	v_lshlrev_b32_e32 v106, 16, v144
	v_and_b32_e32 v107, 0xffff0000, v144
	v_lshlrev_b32_e32 v88, 16, v145
	v_and_b32_e32 v89, 0xffff0000, v145
	v_lshlrev_b32_e32 v92, 16, v146
	v_and_b32_e32 v93, 0xffff0000, v146
	v_lshlrev_b32_e32 v90, 16, v147
	v_and_b32_e32 v91, 0xffff0000, v147
	v_pk_fma_f32 v[94:95], v[30:31], v[80:81], v[96:97]
	v_pk_fma_f32 v[96:97], v[32:33], v[82:83], v[98:99]
	v_pk_fma_f32 v[98:99], v[26:27], v[84:85], v[100:101]
	v_pk_fma_f32 v[100:101], v[28:29], v[86:87], v[102:103]
	v_pk_mul_f32 v[94:95], v[94:95], v[106:107]
	v_pk_mul_f32 v[96:97], v[96:97], v[88:89]
	v_pk_mul_f32 v[92:93], v[98:99], v[92:93]
	v_pk_mul_f32 v[98:99], v[100:101], v[90:91]
	v_cvt_pk_bf16_f32 v88, v94, v95
	v_cvt_pk_bf16_f32 v89, v96, v97
	v_cvt_pk_bf16_f32 v90, v92, v93
	v_cvt_pk_bf16_f32 v91, v98, v99
	global_store_dwordx4 v[104:105], v[88:91], off
	s_add_i32 s4, s1, 4
	s_ashr_i32 s5, s4, 31
	s_lshl_b64 s[4:5], s[4:5], 13
	s_add_u32 s4, s42, s4
	v_mov_b32_e32 v71, v39
	v_pk_mul_f32 v[96:97], v[80:81], v[22:23]
	s_addc_u32 s5, s43, s5
	v_pk_fma_f32 v[96:97], v[72:73], v[14:15], v[96:97]
	v_mov_b32_e32 v72, v80
	v_mov_b32_e32 v73, v81
	v_lshl_add_u64 v[80:81], s[4:5], 0, v[70:71]
	v_pk_mul_f32 v[98:99], v[82:83], v[24:25]
	v_pk_mul_f32 v[100:101], v[84:85], v[18:19]
	v_pk_mul_f32 v[102:103], v[86:87], v[20:21]
	v_add_co_u32_e32 v104, vcc, 0x1000, v80
	v_pk_fma_f32 v[98:99], v[74:75], v[16:17], v[98:99]
	v_pk_fma_f32 v[100:101], v[76:77], v[10:11], v[100:101]
	v_pk_fma_f32 v[102:103], v[78:79], v[12:13], v[102:103]
	v_mov_b32_e32 v74, v82
	v_mov_b32_e32 v75, v83
	v_mov_b32_e32 v76, v84
	v_mov_b32_e32 v77, v85
	v_mov_b32_e32 v78, v86
	v_mov_b32_e32 v79, v87
	v_addc_co_u32_e32 v105, vcc, 0, v81, vcc
	s_waitcnt vmcnt(7)
	v_lshlrev_b32_e32 v80, 16, v148
	v_and_b32_e32 v81, 0xffff0000, v148
	v_lshlrev_b32_e32 v82, 16, v149
	v_and_b32_e32 v83, 0xffff0000, v149
	v_lshlrev_b32_e32 v84, 16, v150
	v_and_b32_e32 v85, 0xffff0000, v150
	v_lshlrev_b32_e32 v86, 16, v151
	v_and_b32_e32 v87, 0xffff0000, v151
	s_waitcnt vmcnt(6)
	v_lshlrev_b32_e32 v106, 16, v152
	v_and_b32_e32 v107, 0xffff0000, v152
	v_lshlrev_b32_e32 v88, 16, v153
	v_and_b32_e32 v89, 0xffff0000, v153
	v_lshlrev_b32_e32 v92, 16, v154
	v_and_b32_e32 v93, 0xffff0000, v154
	v_lshlrev_b32_e32 v90, 16, v155
	v_and_b32_e32 v91, 0xffff0000, v155
	v_pk_fma_f32 v[94:95], v[30:31], v[80:81], v[96:97]
	v_pk_fma_f32 v[96:97], v[32:33], v[82:83], v[98:99]
	v_pk_fma_f32 v[98:99], v[26:27], v[84:85], v[100:101]
	v_pk_fma_f32 v[100:101], v[28:29], v[86:87], v[102:103]
	v_pk_mul_f32 v[94:95], v[94:95], v[106:107]
	v_pk_mul_f32 v[96:97], v[96:97], v[88:89]
	v_pk_mul_f32 v[92:93], v[98:99], v[92:93]
	v_pk_mul_f32 v[98:99], v[100:101], v[90:91]
	v_cvt_pk_bf16_f32 v88, v94, v95
	v_cvt_pk_bf16_f32 v89, v96, v97
	v_cvt_pk_bf16_f32 v90, v92, v93
	v_cvt_pk_bf16_f32 v91, v98, v99
	global_store_dwordx4 v[104:105], v[88:91], off
	s_add_i32 s4, s1, 5
	s_ashr_i32 s5, s4, 31
	s_lshl_b64 s[4:5], s[4:5], 13
	s_add_u32 s4, s42, s4
	v_mov_b32_e32 v71, v39
	v_pk_mul_f32 v[96:97], v[80:81], v[22:23]
	s_addc_u32 s5, s43, s5
	v_pk_fma_f32 v[96:97], v[72:73], v[14:15], v[96:97]
	v_mov_b32_e32 v72, v80
	v_mov_b32_e32 v73, v81
	v_lshl_add_u64 v[80:81], s[4:5], 0, v[70:71]
	v_pk_mul_f32 v[98:99], v[82:83], v[24:25]
	v_pk_mul_f32 v[100:101], v[84:85], v[18:19]
	v_pk_mul_f32 v[102:103], v[86:87], v[20:21]
	v_add_co_u32_e32 v104, vcc, 0x1000, v80
	v_pk_fma_f32 v[98:99], v[74:75], v[16:17], v[98:99]
	v_pk_fma_f32 v[100:101], v[76:77], v[10:11], v[100:101]
	v_pk_fma_f32 v[102:103], v[78:79], v[12:13], v[102:103]
	v_mov_b32_e32 v74, v82
	v_mov_b32_e32 v75, v83
	v_mov_b32_e32 v76, v84
	v_mov_b32_e32 v77, v85
	v_mov_b32_e32 v78, v86
	v_mov_b32_e32 v79, v87
	v_addc_co_u32_e32 v105, vcc, 0, v81, vcc
	s_waitcnt vmcnt(5)
	v_lshlrev_b32_e32 v80, 16, v156
	v_and_b32_e32 v81, 0xffff0000, v156
	v_lshlrev_b32_e32 v82, 16, v157
	v_and_b32_e32 v83, 0xffff0000, v157
	v_lshlrev_b32_e32 v84, 16, v158
	v_and_b32_e32 v85, 0xffff0000, v158
	v_lshlrev_b32_e32 v86, 16, v159
	v_and_b32_e32 v87, 0xffff0000, v159
	s_waitcnt vmcnt(4)
	v_lshlrev_b32_e32 v106, 16, v160
	v_and_b32_e32 v107, 0xffff0000, v160
	v_lshlrev_b32_e32 v88, 16, v161
	v_and_b32_e32 v89, 0xffff0000, v161
	v_lshlrev_b32_e32 v92, 16, v162
	v_and_b32_e32 v93, 0xffff0000, v162
	v_lshlrev_b32_e32 v90, 16, v163
	v_and_b32_e32 v91, 0xffff0000, v163
	v_pk_fma_f32 v[94:95], v[30:31], v[80:81], v[96:97]
	v_pk_fma_f32 v[96:97], v[32:33], v[82:83], v[98:99]
	v_pk_fma_f32 v[98:99], v[26:27], v[84:85], v[100:101]
	v_pk_fma_f32 v[100:101], v[28:29], v[86:87], v[102:103]
	v_pk_mul_f32 v[94:95], v[94:95], v[106:107]
	v_pk_mul_f32 v[96:97], v[96:97], v[88:89]
	v_pk_mul_f32 v[92:93], v[98:99], v[92:93]
	v_pk_mul_f32 v[98:99], v[100:101], v[90:91]
	v_cvt_pk_bf16_f32 v88, v94, v95
	v_cvt_pk_bf16_f32 v89, v96, v97
	v_cvt_pk_bf16_f32 v90, v92, v93
	v_cvt_pk_bf16_f32 v91, v98, v99
	global_store_dwordx4 v[104:105], v[88:91], off
	s_add_i32 s4, s1, 6
	s_ashr_i32 s5, s4, 31
	s_lshl_b64 s[4:5], s[4:5], 13
	s_add_u32 s4, s42, s4
	v_mov_b32_e32 v71, v39
	v_pk_mul_f32 v[96:97], v[80:81], v[22:23]
	s_addc_u32 s5, s43, s5
	v_pk_fma_f32 v[96:97], v[72:73], v[14:15], v[96:97]
	v_mov_b32_e32 v72, v80
	v_mov_b32_e32 v73, v81
	v_lshl_add_u64 v[80:81], s[4:5], 0, v[70:71]
	v_pk_mul_f32 v[98:99], v[82:83], v[24:25]
	v_pk_mul_f32 v[100:101], v[84:85], v[18:19]
	v_pk_mul_f32 v[102:103], v[86:87], v[20:21]
	v_add_co_u32_e32 v104, vcc, 0x1000, v80
	v_pk_fma_f32 v[98:99], v[74:75], v[16:17], v[98:99]
	v_pk_fma_f32 v[100:101], v[76:77], v[10:11], v[100:101]
	v_pk_fma_f32 v[102:103], v[78:79], v[12:13], v[102:103]
	v_mov_b32_e32 v74, v82
	v_mov_b32_e32 v75, v83
	v_mov_b32_e32 v76, v84
	v_mov_b32_e32 v77, v85
	v_mov_b32_e32 v78, v86
	v_mov_b32_e32 v79, v87
	v_addc_co_u32_e32 v105, vcc, 0, v81, vcc
	s_waitcnt vmcnt(3)
	v_lshlrev_b32_e32 v80, 16, v164
	v_and_b32_e32 v81, 0xffff0000, v164
	v_lshlrev_b32_e32 v82, 16, v165
	v_and_b32_e32 v83, 0xffff0000, v165
	v_lshlrev_b32_e32 v84, 16, v166
	v_and_b32_e32 v85, 0xffff0000, v166
	v_lshlrev_b32_e32 v86, 16, v167
	v_and_b32_e32 v87, 0xffff0000, v167
	s_waitcnt vmcnt(2)
	v_lshlrev_b32_e32 v106, 16, v168
	v_and_b32_e32 v107, 0xffff0000, v168
	v_lshlrev_b32_e32 v88, 16, v169
	v_and_b32_e32 v89, 0xffff0000, v169
	v_lshlrev_b32_e32 v92, 16, v170
	v_and_b32_e32 v93, 0xffff0000, v170
	v_lshlrev_b32_e32 v90, 16, v171
	v_and_b32_e32 v91, 0xffff0000, v171
	v_pk_fma_f32 v[94:95], v[30:31], v[80:81], v[96:97]
	v_pk_fma_f32 v[96:97], v[32:33], v[82:83], v[98:99]
	v_pk_fma_f32 v[98:99], v[26:27], v[84:85], v[100:101]
	v_pk_fma_f32 v[100:101], v[28:29], v[86:87], v[102:103]
	v_pk_mul_f32 v[94:95], v[94:95], v[106:107]
	v_pk_mul_f32 v[96:97], v[96:97], v[88:89]
	v_pk_mul_f32 v[92:93], v[98:99], v[92:93]
	v_pk_mul_f32 v[98:99], v[100:101], v[90:91]
	v_cvt_pk_bf16_f32 v88, v94, v95
	v_cvt_pk_bf16_f32 v89, v96, v97
	v_cvt_pk_bf16_f32 v90, v92, v93
	v_cvt_pk_bf16_f32 v91, v98, v99
	global_store_dwordx4 v[104:105], v[88:91], off
	s_add_i32 s4, s1, 7
	s_ashr_i32 s5, s4, 31
	s_lshl_b64 s[4:5], s[4:5], 13
	s_add_u32 s4, s42, s4
	v_mov_b32_e32 v71, v39
	v_pk_mul_f32 v[96:97], v[80:81], v[22:23]
	s_addc_u32 s5, s43, s5
	v_pk_fma_f32 v[96:97], v[72:73], v[14:15], v[96:97]
	v_mov_b32_e32 v72, v80
	v_mov_b32_e32 v73, v81
	v_lshl_add_u64 v[80:81], s[4:5], 0, v[70:71]
	v_pk_mul_f32 v[98:99], v[82:83], v[24:25]
	v_pk_mul_f32 v[100:101], v[84:85], v[18:19]
	v_pk_mul_f32 v[102:103], v[86:87], v[20:21]
	v_add_co_u32_e32 v104, vcc, 0x1000, v80
	v_pk_fma_f32 v[98:99], v[74:75], v[16:17], v[98:99]
	v_pk_fma_f32 v[100:101], v[76:77], v[10:11], v[100:101]
	v_pk_fma_f32 v[102:103], v[78:79], v[12:13], v[102:103]
	v_mov_b32_e32 v74, v82
	v_mov_b32_e32 v75, v83
	v_mov_b32_e32 v76, v84
	v_mov_b32_e32 v77, v85
	v_mov_b32_e32 v78, v86
	v_mov_b32_e32 v79, v87
	v_addc_co_u32_e32 v105, vcc, 0, v81, vcc
	s_waitcnt vmcnt(1)
	v_lshlrev_b32_e32 v80, 16, v172
	v_and_b32_e32 v81, 0xffff0000, v172
	v_lshlrev_b32_e32 v82, 16, v173
	v_and_b32_e32 v83, 0xffff0000, v173
	v_lshlrev_b32_e32 v84, 16, v174
	v_and_b32_e32 v85, 0xffff0000, v174
	v_lshlrev_b32_e32 v86, 16, v175
	v_and_b32_e32 v87, 0xffff0000, v175
	s_waitcnt vmcnt(0)
	v_lshlrev_b32_e32 v106, 16, v176
	v_and_b32_e32 v107, 0xffff0000, v176
	v_lshlrev_b32_e32 v88, 16, v177
	v_and_b32_e32 v89, 0xffff0000, v177
	v_lshlrev_b32_e32 v92, 16, v178
	v_and_b32_e32 v93, 0xffff0000, v178
	v_lshlrev_b32_e32 v90, 16, v179
	v_and_b32_e32 v91, 0xffff0000, v179
	v_pk_fma_f32 v[94:95], v[30:31], v[80:81], v[96:97]
	v_pk_fma_f32 v[96:97], v[32:33], v[82:83], v[98:99]
	v_pk_fma_f32 v[98:99], v[26:27], v[84:85], v[100:101]
	v_pk_fma_f32 v[100:101], v[28:29], v[86:87], v[102:103]
	v_pk_mul_f32 v[94:95], v[94:95], v[106:107]
	v_pk_mul_f32 v[96:97], v[96:97], v[88:89]
	v_pk_mul_f32 v[92:93], v[98:99], v[92:93]
	v_pk_mul_f32 v[98:99], v[100:101], v[90:91]
	v_cvt_pk_bf16_f32 v88, v94, v95
	v_cvt_pk_bf16_f32 v89, v96, v97
	v_cvt_pk_bf16_f32 v90, v92, v93
	v_cvt_pk_bf16_f32 v91, v98, v99
	global_store_dwordx4 v[104:105], v[88:91], off
	s_mov_b32 s6, 8
	s_add_i32 s0, s0, s56
	s_add_i32 s1, s1, s3
	s_cmpk_gt_i32 s0, 0x7ff
	s_cbranch_scc0 .LBB0_416
